# up-projection epilogue: conv weights prefetched during the last k-steps; fast row path (8 consecutive rows per lane group, taps unpacked once, shared reciprocal) for tiles without a sequence boundary
# speedup vs baseline: 1.0995x; 1.0133x over previous
.Lg_up_loop:
	ds_read_b128 v[198:201], v134 offset:8192
	ds_read_b128 v[202:205], v134 offset:10240
	ds_read_b128 v[206:209], v134 offset:12288
	ds_read_b128 v[210:213], v134 offset:14336
	s_waitcnt lgkmcnt(4)
	v_mfma_f32_16x16x32_bf16 v[124:127], v[168:171], v[152:155], v[124:127]
	v_mfma_f32_16x16x32_bf16 v[120:123], v[168:171], v[156:159], v[120:123]
	v_mfma_f32_16x16x32_bf16 v[116:119], v[168:171], v[160:163], v[116:119]
	v_mfma_f32_16x16x32_bf16 v[112:115], v[168:171], v[164:167], v[112:115]
	v_mfma_f32_16x16x32_bf16 v[108:111], v[172:175], v[152:155], v[108:111]
	v_mfma_f32_16x16x32_bf16 v[104:107], v[172:175], v[156:159], v[104:107]
	v_mfma_f32_16x16x32_bf16 v[100:103], v[172:175], v[160:163], v[100:103]
	v_mfma_f32_16x16x32_bf16 v[96:99], v[172:175], v[164:167], v[96:99]
	v_mfma_f32_16x16x32_bf16 v[92:95], v[176:179], v[152:155], v[92:95]
	v_mfma_f32_16x16x32_bf16 v[84:87], v[176:179], v[156:159], v[84:87]
	v_mfma_f32_16x16x32_bf16 v[80:83], v[176:179], v[160:163], v[80:83]
	v_mfma_f32_16x16x32_bf16 v[76:79], v[176:179], v[164:167], v[76:79]
	v_mfma_f32_16x16x32_bf16 v[72:75], v[180:183], v[152:155], v[72:75]
	v_mfma_f32_16x16x32_bf16 v[68:71], v[180:183], v[156:159], v[68:71]
	v_mfma_f32_16x16x32_bf16 v[64:67], v[180:183], v[160:163], v[64:67]
	v_mfma_f32_16x16x32_bf16 v[60:63], v[180:183], v[164:167], v[60:63]
	v_add_u32_e32 v180, v149, v150
	v_add_u32_e32 v134, v149, v148
	ds_read_b128 v[168:171], v180 offset:32768
	ds_read_b128 v[172:175], v180 offset:34816
	ds_read_b128 v[176:179], v180 offset:36864
	ds_read_b128 v[180:183], v180 offset:38912
	ds_read_b128 v[214:217], v134 offset:0
	ds_read_b128 v[218:221], v134 offset:2048
	ds_read_b128 v[222:225], v134 offset:4096
	ds_read_b128 v[226:229], v134 offset:6144
	s_waitcnt lgkmcnt(8)
	v_mfma_f32_16x16x32_bf16 v[56:59], v[198:201], v[152:155], v[56:59]
	v_mfma_f32_16x16x32_bf16 v[52:55], v[198:201], v[156:159], v[52:55]
	v_mfma_f32_16x16x32_bf16 v[48:51], v[198:201], v[160:163], v[48:51]
	v_mfma_f32_16x16x32_bf16 v[44:47], v[198:201], v[164:167], v[44:47]
	v_mfma_f32_16x16x32_bf16 v[40:43], v[202:205], v[152:155], v[40:43]
	v_mfma_f32_16x16x32_bf16 v[36:39], v[202:205], v[156:159], v[36:39]
	v_mfma_f32_16x16x32_bf16 v[32:35], v[202:205], v[160:163], v[32:35]
	v_mfma_f32_16x16x32_bf16 v[28:31], v[202:205], v[164:167], v[28:31]
	v_mfma_f32_16x16x32_bf16 v[24:27], v[206:209], v[152:155], v[24:27]
	v_mfma_f32_16x16x32_bf16 v[20:23], v[206:209], v[156:159], v[20:23]
	v_mfma_f32_16x16x32_bf16 v[16:19], v[206:209], v[160:163], v[16:19]
	v_mfma_f32_16x16x32_bf16 v[12:15], v[206:209], v[164:167], v[12:15]
	v_mfma_f32_16x16x32_bf16 v[8:11], v[210:213], v[152:155], v[8:11]
	v_mfma_f32_16x16x32_bf16 v[4:7], v[210:213], v[156:159], v[4:7]
	v_mfma_f32_16x16x32_bf16 v[0:3], v[210:213], v[160:163], v[0:3]
	v_mfma_f32_16x16x32_bf16 v[88:91], v[210:213], v[164:167], v[88:91]
	ds_read_b128 v[152:155], v134 offset:8192
	ds_read_b128 v[156:159], v134 offset:10240
	ds_read_b128 v[160:163], v134 offset:12288
	ds_read_b128 v[164:167], v134 offset:14336
	s_waitcnt lgkmcnt(4)
	v_mfma_f32_16x16x32_bf16 v[124:127], v[214:217], v[168:171], v[124:127]
	v_mfma_f32_16x16x32_bf16 v[120:123], v[214:217], v[172:175], v[120:123]
	v_mfma_f32_16x16x32_bf16 v[116:119], v[214:217], v[176:179], v[116:119]
	v_mfma_f32_16x16x32_bf16 v[112:115], v[214:217], v[180:183], v[112:115]
	v_mfma_f32_16x16x32_bf16 v[108:111], v[218:221], v[168:171], v[108:111]
	v_mfma_f32_16x16x32_bf16 v[104:107], v[218:221], v[172:175], v[104:107]
	v_mfma_f32_16x16x32_bf16 v[100:103], v[218:221], v[176:179], v[100:103]
	v_mfma_f32_16x16x32_bf16 v[96:99], v[218:221], v[180:183], v[96:99]
	v_mfma_f32_16x16x32_bf16 v[92:95], v[222:225], v[168:171], v[92:95]
	v_mfma_f32_16x16x32_bf16 v[84:87], v[222:225], v[172:175], v[84:87]
	v_mfma_f32_16x16x32_bf16 v[80:83], v[222:225], v[176:179], v[80:83]
	v_mfma_f32_16x16x32_bf16 v[76:79], v[222:225], v[180:183], v[76:79]
	v_mfma_f32_16x16x32_bf16 v[72:75], v[226:229], v[168:171], v[72:75]
	v_mfma_f32_16x16x32_bf16 v[68:71], v[226:229], v[172:175], v[68:71]
	v_mfma_f32_16x16x32_bf16 v[64:67], v[226:229], v[176:179], v[64:67]
	v_mfma_f32_16x16x32_bf16 v[60:63], v[226:229], v[180:183], v[60:63]
	s_waitcnt lgkmcnt(0)
	v_mfma_f32_16x16x32_bf16 v[56:59], v[152:155], v[168:171], v[56:59]
	s_waitcnt vmcnt(0)
	s_barrier
	v_add3_u32 v210, v151, v150, s99
	v_add3_u32 v134, v151, v148, s99
	v_mfma_f32_16x16x32_bf16 v[52:55], v[152:155], v[172:175], v[52:55]
	ds_read_b128 v[198:201], v210 offset:32768
	ds_read_b128 v[202:205], v210 offset:34816
	v_mfma_f32_16x16x32_bf16 v[48:51], v[152:155], v[176:179], v[48:51]
	ds_read_b128 v[206:209], v210 offset:36864
	ds_read_b128 v[210:213], v210 offset:38912
	v_mfma_f32_16x16x32_bf16 v[44:47], v[152:155], v[180:183], v[44:47]
	ds_read_b128 v[214:217], v134 offset:0
	ds_read_b128 v[218:221], v134 offset:2048
	v_mfma_f32_16x16x32_bf16 v[40:43], v[156:159], v[168:171], v[40:43]
	ds_read_b128 v[222:225], v134 offset:4096
	ds_read_b128 v[226:229], v134 offset:6144
	s_mov_b32 m0, s93
	v_mfma_f32_16x16x32_bf16 v[36:39], v[156:159], v[172:175], v[36:39]
	global_load_lds_dwordx4 v[128:129], off
	v_lshl_add_u64 v[128:129], v[128:129], 0, s[100:101]
	s_add_i32 m0, s93, 0x8000
	v_mfma_f32_16x16x32_bf16 v[32:35], v[156:159], v[176:179], v[32:35]
	global_load_lds_dwordx4 v[140:141], off
	v_lshl_add_u64 v[140:141], v[140:141], 0, s[100:101]
	s_mov_b32 m0, s94
	v_mfma_f32_16x16x32_bf16 v[28:31], v[156:159], v[180:183], v[28:31]
	global_load_lds_dwordx4 v[130:131], off
	v_lshl_add_u64 v[130:131], v[130:131], 0, s[100:101]
	s_add_i32 m0, s94, 0x8000
	v_mfma_f32_16x16x32_bf16 v[24:27], v[160:163], v[168:171], v[24:27]
	global_load_lds_dwordx4 v[142:143], off
	v_lshl_add_u64 v[142:143], v[142:143], 0, s[100:101]
	s_mov_b32 m0, s95
	v_mfma_f32_16x16x32_bf16 v[20:23], v[160:163], v[172:175], v[20:23]
	global_load_lds_dwordx4 v[136:137], off
	v_lshl_add_u64 v[136:137], v[136:137], 0, s[100:101]
	s_add_i32 m0, s95, 0x8000
	v_mfma_f32_16x16x32_bf16 v[16:19], v[160:163], v[176:179], v[16:19]
	global_load_lds_dwordx4 v[144:145], off
	v_lshl_add_u64 v[144:145], v[144:145], 0, s[100:101]
	s_mov_b32 m0, s96
	v_mfma_f32_16x16x32_bf16 v[12:15], v[160:163], v[180:183], v[12:15]
	global_load_lds_dwordx4 v[138:139], off
	v_lshl_add_u64 v[138:139], v[138:139], 0, s[100:101]
	s_add_i32 m0, s96, 0x8000
	v_mfma_f32_16x16x32_bf16 v[8:11], v[164:167], v[168:171], v[8:11]
	global_load_lds_dwordx4 v[146:147], off
	v_lshl_add_u64 v[146:147], v[146:147], 0, s[100:101]
	v_mfma_f32_16x16x32_bf16 v[4:7], v[164:167], v[172:175], v[4:7]
	v_mfma_f32_16x16x32_bf16 v[0:3], v[164:167], v[176:179], v[0:3]
	v_mfma_f32_16x16x32_bf16 v[88:91], v[164:167], v[180:183], v[88:91]
	ds_read_b128 v[152:155], v134 offset:8192
	ds_read_b128 v[156:159], v134 offset:10240
	ds_read_b128 v[160:163], v134 offset:12288
	ds_read_b128 v[164:167], v134 offset:14336
	s_waitcnt lgkmcnt(4)
	v_mfma_f32_16x16x32_bf16 v[124:127], v[214:217], v[198:201], v[124:127]
	v_mfma_f32_16x16x32_bf16 v[120:123], v[214:217], v[202:205], v[120:123]
	v_mfma_f32_16x16x32_bf16 v[116:119], v[214:217], v[206:209], v[116:119]
	v_mfma_f32_16x16x32_bf16 v[112:115], v[214:217], v[210:213], v[112:115]
	v_mfma_f32_16x16x32_bf16 v[108:111], v[218:221], v[198:201], v[108:111]
	v_mfma_f32_16x16x32_bf16 v[104:107], v[218:221], v[202:205], v[104:107]
	v_mfma_f32_16x16x32_bf16 v[100:103], v[218:221], v[206:209], v[100:103]
	v_mfma_f32_16x16x32_bf16 v[96:99], v[218:221], v[210:213], v[96:99]
	v_mfma_f32_16x16x32_bf16 v[92:95], v[222:225], v[198:201], v[92:95]
	v_mfma_f32_16x16x32_bf16 v[84:87], v[222:225], v[202:205], v[84:87]
	v_mfma_f32_16x16x32_bf16 v[80:83], v[222:225], v[206:209], v[80:83]
	v_mfma_f32_16x16x32_bf16 v[76:79], v[222:225], v[210:213], v[76:79]
	v_mfma_f32_16x16x32_bf16 v[72:75], v[226:229], v[198:201], v[72:75]
	v_mfma_f32_16x16x32_bf16 v[68:71], v[226:229], v[202:205], v[68:71]
	v_mfma_f32_16x16x32_bf16 v[64:67], v[226:229], v[206:209], v[64:67]
	v_mfma_f32_16x16x32_bf16 v[60:63], v[226:229], v[210:213], v[60:63]
	v_add3_u32 v226, v149, v150, s99
	v_add3_u32 v134, v149, v148, s99
	ds_read_b128 v[214:217], v226 offset:32768
	ds_read_b128 v[218:221], v226 offset:34816
	ds_read_b128 v[222:225], v226 offset:36864
	ds_read_b128 v[226:229], v226 offset:38912
	ds_read_b128 v[168:171], v134 offset:0
	ds_read_b128 v[172:175], v134 offset:2048
	ds_read_b128 v[176:179], v134 offset:4096
	ds_read_b128 v[180:183], v134 offset:6144
	s_waitcnt lgkmcnt(8)
	v_mfma_f32_16x16x32_bf16 v[56:59], v[152:155], v[198:201], v[56:59]
	v_mfma_f32_16x16x32_bf16 v[52:55], v[152:155], v[202:205], v[52:55]
	v_mfma_f32_16x16x32_bf16 v[48:51], v[152:155], v[206:209], v[48:51]
	v_mfma_f32_16x16x32_bf16 v[44:47], v[152:155], v[210:213], v[44:47]
	v_mfma_f32_16x16x32_bf16 v[40:43], v[156:159], v[198:201], v[40:43]
	v_mfma_f32_16x16x32_bf16 v[36:39], v[156:159], v[202:205], v[36:39]
	v_mfma_f32_16x16x32_bf16 v[32:35], v[156:159], v[206:209], v[32:35]
	v_mfma_f32_16x16x32_bf16 v[28:31], v[156:159], v[210:213], v[28:31]
	v_mfma_f32_16x16x32_bf16 v[24:27], v[160:163], v[198:201], v[24:27]
	v_mfma_f32_16x16x32_bf16 v[20:23], v[160:163], v[202:205], v[20:23]
	v_mfma_f32_16x16x32_bf16 v[16:19], v[160:163], v[206:209], v[16:19]
	v_mfma_f32_16x16x32_bf16 v[12:15], v[160:163], v[210:213], v[12:15]
	v_mfma_f32_16x16x32_bf16 v[8:11], v[164:167], v[198:201], v[8:11]
	v_mfma_f32_16x16x32_bf16 v[4:7], v[164:167], v[202:205], v[4:7]
	v_mfma_f32_16x16x32_bf16 v[0:3], v[164:167], v[206:209], v[0:3]
	v_mfma_f32_16x16x32_bf16 v[88:91], v[164:167], v[210:213], v[88:91]
	ds_read_b128 v[198:201], v134 offset:8192
	ds_read_b128 v[202:205], v134 offset:10240
	ds_read_b128 v[206:209], v134 offset:12288
	ds_read_b128 v[210:213], v134 offset:14336
	s_waitcnt lgkmcnt(4)
	v_mfma_f32_16x16x32_bf16 v[124:127], v[168:171], v[214:217], v[124:127]
	v_mfma_f32_16x16x32_bf16 v[120:123], v[168:171], v[218:221], v[120:123]
	v_mfma_f32_16x16x32_bf16 v[116:119], v[168:171], v[222:225], v[116:119]
	v_mfma_f32_16x16x32_bf16 v[112:115], v[168:171], v[226:229], v[112:115]
	v_mfma_f32_16x16x32_bf16 v[108:111], v[172:175], v[214:217], v[108:111]
	v_mfma_f32_16x16x32_bf16 v[104:107], v[172:175], v[218:221], v[104:107]
	v_mfma_f32_16x16x32_bf16 v[100:103], v[172:175], v[222:225], v[100:103]
	v_mfma_f32_16x16x32_bf16 v[96:99], v[172:175], v[226:229], v[96:99]
	v_mfma_f32_16x16x32_bf16 v[92:95], v[176:179], v[214:217], v[92:95]
	v_mfma_f32_16x16x32_bf16 v[84:87], v[176:179], v[218:221], v[84:87]
	v_mfma_f32_16x16x32_bf16 v[80:83], v[176:179], v[222:225], v[80:83]
	v_mfma_f32_16x16x32_bf16 v[76:79], v[176:179], v[226:229], v[76:79]
	v_mfma_f32_16x16x32_bf16 v[72:75], v[180:183], v[214:217], v[72:75]
	v_mfma_f32_16x16x32_bf16 v[68:71], v[180:183], v[218:221], v[68:71]
	v_mfma_f32_16x16x32_bf16 v[64:67], v[180:183], v[222:225], v[64:67]
	v_mfma_f32_16x16x32_bf16 v[60:63], v[180:183], v[226:229], v[60:63]
	s_waitcnt lgkmcnt(0)
	v_mfma_f32_16x16x32_bf16 v[56:59], v[198:201], v[214:217], v[56:59]
	s_waitcnt vmcnt(0)
	s_barrier
	v_add_u32_e32 v164, v151, v150
	v_add_u32_e32 v134, v151, v148
	v_mfma_f32_16x16x32_bf16 v[52:55], v[198:201], v[218:221], v[52:55]
	ds_read_b128 v[152:155], v164 offset:32768
	ds_read_b128 v[156:159], v164 offset:34816
	v_mfma_f32_16x16x32_bf16 v[48:51], v[198:201], v[222:225], v[48:51]
	ds_read_b128 v[160:163], v164 offset:36864
	ds_read_b128 v[164:167], v164 offset:38912
	v_mfma_f32_16x16x32_bf16 v[44:47], v[198:201], v[226:229], v[44:47]
	ds_read_b128 v[168:171], v134 offset:0
	ds_read_b128 v[172:175], v134 offset:2048
	v_mfma_f32_16x16x32_bf16 v[40:43], v[202:205], v[214:217], v[40:43]
	ds_read_b128 v[176:179], v134 offset:4096
	ds_read_b128 v[180:183], v134 offset:6144
	s_add_i32 m0, s93, 0x10000
	v_mfma_f32_16x16x32_bf16 v[36:39], v[202:205], v[218:221], v[36:39]
	global_load_lds_dwordx4 v[128:129], off
	v_lshl_add_u64 v[128:129], v[128:129], 0, s[100:101]
	s_add_i32 m0, s93, 0x18000
	v_mfma_f32_16x16x32_bf16 v[32:35], v[202:205], v[222:225], v[32:35]
	global_load_lds_dwordx4 v[140:141], off
	v_lshl_add_u64 v[140:141], v[140:141], 0, s[100:101]
	s_add_i32 m0, s94, 0x10000
	v_mfma_f32_16x16x32_bf16 v[28:31], v[202:205], v[226:229], v[28:31]
	global_load_lds_dwordx4 v[130:131], off
	v_lshl_add_u64 v[130:131], v[130:131], 0, s[100:101]
	s_add_i32 m0, s94, 0x18000
	v_mfma_f32_16x16x32_bf16 v[24:27], v[206:209], v[214:217], v[24:27]
	global_load_lds_dwordx4 v[142:143], off
	v_lshl_add_u64 v[142:143], v[142:143], 0, s[100:101]
	s_add_i32 m0, s95, 0x10000
	v_mfma_f32_16x16x32_bf16 v[20:23], v[206:209], v[218:221], v[20:23]
	global_load_lds_dwordx4 v[136:137], off
	v_lshl_add_u64 v[136:137], v[136:137], 0, s[100:101]
	s_add_i32 m0, s95, 0x18000
	v_mfma_f32_16x16x32_bf16 v[16:19], v[206:209], v[222:225], v[16:19]
	global_load_lds_dwordx4 v[144:145], off
	v_lshl_add_u64 v[144:145], v[144:145], 0, s[100:101]
	s_add_i32 m0, s96, 0x10000
	v_mfma_f32_16x16x32_bf16 v[12:15], v[206:209], v[226:229], v[12:15]
	global_load_lds_dwordx4 v[138:139], off
	v_lshl_add_u64 v[138:139], v[138:139], 0, s[100:101]
	s_add_i32 m0, s96, 0x18000
	v_mfma_f32_16x16x32_bf16 v[8:11], v[210:213], v[214:217], v[8:11]
	global_load_lds_dwordx4 v[146:147], off
	v_lshl_add_u64 v[146:147], v[146:147], 0, s[100:101]
	v_mfma_f32_16x16x32_bf16 v[4:7], v[210:213], v[218:221], v[4:7]
	v_mfma_f32_16x16x32_bf16 v[0:3], v[210:213], v[222:225], v[0:3]
	v_mfma_f32_16x16x32_bf16 v[88:91], v[210:213], v[226:229], v[88:91]
	s_add_u32 s2, s2, 0x100
	s_cmpk_lg_i32 s2, 0x700
	s_cbranch_scc1 .Lg_up_loop
	ds_read_b128 v[198:201], v134 offset:8192
	ds_read_b128 v[202:205], v134 offset:10240
	ds_read_b128 v[206:209], v134 offset:12288
	ds_read_b128 v[210:213], v134 offset:14336
	s_waitcnt lgkmcnt(4)
	v_mfma_f32_16x16x32_bf16 v[124:127], v[168:171], v[152:155], v[124:127]
	v_mfma_f32_16x16x32_bf16 v[120:123], v[168:171], v[156:159], v[120:123]
	v_mfma_f32_16x16x32_bf16 v[116:119], v[168:171], v[160:163], v[116:119]
	v_mfma_f32_16x16x32_bf16 v[112:115], v[168:171], v[164:167], v[112:115]
	v_mfma_f32_16x16x32_bf16 v[108:111], v[172:175], v[152:155], v[108:111]
	v_mfma_f32_16x16x32_bf16 v[104:107], v[172:175], v[156:159], v[104:107]
	v_mfma_f32_16x16x32_bf16 v[100:103], v[172:175], v[160:163], v[100:103]
	v_mfma_f32_16x16x32_bf16 v[96:99], v[172:175], v[164:167], v[96:99]
	v_mfma_f32_16x16x32_bf16 v[92:95], v[176:179], v[152:155], v[92:95]
	v_mfma_f32_16x16x32_bf16 v[84:87], v[176:179], v[156:159], v[84:87]
	v_mfma_f32_16x16x32_bf16 v[80:83], v[176:179], v[160:163], v[80:83]
	v_mfma_f32_16x16x32_bf16 v[76:79], v[176:179], v[164:167], v[76:79]
	v_mfma_f32_16x16x32_bf16 v[72:75], v[180:183], v[152:155], v[72:75]
	v_mfma_f32_16x16x32_bf16 v[68:71], v[180:183], v[156:159], v[68:71]
	v_mfma_f32_16x16x32_bf16 v[64:67], v[180:183], v[160:163], v[64:67]
	v_mfma_f32_16x16x32_bf16 v[60:63], v[180:183], v[164:167], v[60:63]
	v_add_u32_e32 v180, v149, v150
	v_add_u32_e32 v134, v149, v148
	ds_read_b128 v[168:171], v180 offset:32768
	ds_read_b128 v[172:175], v180 offset:34816
	ds_read_b128 v[176:179], v180 offset:36864
	ds_read_b128 v[180:183], v180 offset:38912
	ds_read_b128 v[214:217], v134 offset:0
	ds_read_b128 v[218:221], v134 offset:2048
	ds_read_b128 v[222:225], v134 offset:4096
	ds_read_b128 v[226:229], v134 offset:6144
	s_waitcnt lgkmcnt(8)
	v_mfma_f32_16x16x32_bf16 v[56:59], v[198:201], v[152:155], v[56:59]
	v_mfma_f32_16x16x32_bf16 v[52:55], v[198:201], v[156:159], v[52:55]
	v_mfma_f32_16x16x32_bf16 v[48:51], v[198:201], v[160:163], v[48:51]
	v_mfma_f32_16x16x32_bf16 v[44:47], v[198:201], v[164:167], v[44:47]
	v_mfma_f32_16x16x32_bf16 v[40:43], v[202:205], v[152:155], v[40:43]
	v_mfma_f32_16x16x32_bf16 v[36:39], v[202:205], v[156:159], v[36:39]
	v_mfma_f32_16x16x32_bf16 v[32:35], v[202:205], v[160:163], v[32:35]
	v_mfma_f32_16x16x32_bf16 v[28:31], v[202:205], v[164:167], v[28:31]
	v_mfma_f32_16x16x32_bf16 v[24:27], v[206:209], v[152:155], v[24:27]
	v_mfma_f32_16x16x32_bf16 v[20:23], v[206:209], v[156:159], v[20:23]
	v_mfma_f32_16x16x32_bf16 v[16:19], v[206:209], v[160:163], v[16:19]
	v_mfma_f32_16x16x32_bf16 v[12:15], v[206:209], v[164:167], v[12:15]
	v_mfma_f32_16x16x32_bf16 v[8:11], v[210:213], v[152:155], v[8:11]
	v_mfma_f32_16x16x32_bf16 v[4:7], v[210:213], v[156:159], v[4:7]
	v_mfma_f32_16x16x32_bf16 v[0:3], v[210:213], v[160:163], v[0:3]
	v_mfma_f32_16x16x32_bf16 v[88:91], v[210:213], v[164:167], v[88:91]
	ds_read_b128 v[152:155], v134 offset:8192
	ds_read_b128 v[156:159], v134 offset:10240
	ds_read_b128 v[160:163], v134 offset:12288
	ds_read_b128 v[164:167], v134 offset:14336
	s_waitcnt lgkmcnt(4)
	v_mfma_f32_16x16x32_bf16 v[124:127], v[214:217], v[168:171], v[124:127]
	v_mfma_f32_16x16x32_bf16 v[120:123], v[214:217], v[172:175], v[120:123]
	v_mfma_f32_16x16x32_bf16 v[116:119], v[214:217], v[176:179], v[116:119]
	v_mfma_f32_16x16x32_bf16 v[112:115], v[214:217], v[180:183], v[112:115]
	v_mfma_f32_16x16x32_bf16 v[108:111], v[218:221], v[168:171], v[108:111]
	v_mfma_f32_16x16x32_bf16 v[104:107], v[218:221], v[172:175], v[104:107]
	v_mfma_f32_16x16x32_bf16 v[100:103], v[218:221], v[176:179], v[100:103]
	v_mfma_f32_16x16x32_bf16 v[96:99], v[218:221], v[180:183], v[96:99]
	v_mfma_f32_16x16x32_bf16 v[92:95], v[222:225], v[168:171], v[92:95]
	v_mfma_f32_16x16x32_bf16 v[84:87], v[222:225], v[172:175], v[84:87]
	v_mfma_f32_16x16x32_bf16 v[80:83], v[222:225], v[176:179], v[80:83]
	v_mfma_f32_16x16x32_bf16 v[76:79], v[222:225], v[180:183], v[76:79]
	v_mfma_f32_16x16x32_bf16 v[72:75], v[226:229], v[168:171], v[72:75]
	v_mfma_f32_16x16x32_bf16 v[68:71], v[226:229], v[172:175], v[68:71]
	v_mfma_f32_16x16x32_bf16 v[64:67], v[226:229], v[176:179], v[64:67]
	v_mfma_f32_16x16x32_bf16 v[60:63], v[226:229], v[180:183], v[60:63]
	s_waitcnt lgkmcnt(0)
	v_mfma_f32_16x16x32_bf16 v[56:59], v[152:155], v[168:171], v[56:59]
	s_waitcnt vmcnt(0)
	s_barrier
	v_lshlrev_b32_e32 v254, 3, v184
	v_and_b32_e32 v254, 0x78, v254
	v_lshl_or_b32 v254, s44, 7, v254
	v_lshlrev_b32_e32 v254, 2, v254
	v_add_u32_e32 v222, 0x2c00, v254
	v_add_u32_e32 v223, 0x5800, v254
	global_load_dwordx4 v[234:237], v254, s[10:11]
	global_load_dwordx4 v[230:233], v254, s[10:11] offset:16
	global_load_dwordx4 v[238:241], v222, s[10:11]
	global_load_dwordx4 v[242:245], v222, s[10:11] offset:16
	global_load_dwordx4 v[246:249], v223, s[10:11]
	global_load_dwordx4 v[250:253], v223, s[10:11] offset:16
	global_load_dwordx4 v[214:217], v254, s[12:13] offset:16
	global_load_dwordx4 v[218:221], v254, s[12:13]
	v_mfma_f32_16x16x32_bf16 v[52:55], v[152:155], v[172:175], v[52:55]
	v_mfma_f32_16x16x32_bf16 v[48:51], v[152:155], v[176:179], v[48:51]
	v_mfma_f32_16x16x32_bf16 v[44:47], v[152:155], v[180:183], v[44:47]
	v_mfma_f32_16x16x32_bf16 v[40:43], v[156:159], v[168:171], v[40:43]
	v_mfma_f32_16x16x32_bf16 v[36:39], v[156:159], v[172:175], v[36:39]
	v_mfma_f32_16x16x32_bf16 v[32:35], v[156:159], v[176:179], v[32:35]
	v_mfma_f32_16x16x32_bf16 v[28:31], v[156:159], v[180:183], v[28:31]
	v_mfma_f32_16x16x32_bf16 v[24:27], v[160:163], v[168:171], v[24:27]
	v_mfma_f32_16x16x32_bf16 v[20:23], v[160:163], v[172:175], v[20:23]
	v_mfma_f32_16x16x32_bf16 v[16:19], v[160:163], v[176:179], v[16:19]
	v_mfma_f32_16x16x32_bf16 v[12:15], v[160:163], v[180:183], v[12:15]
	v_mfma_f32_16x16x32_bf16 v[8:11], v[164:167], v[168:171], v[8:11]
	v_mfma_f32_16x16x32_bf16 v[4:7], v[164:167], v[172:175], v[4:7]
	v_mfma_f32_16x16x32_bf16 v[0:3], v[164:167], v[176:179], v[0:3]
	v_mfma_f32_16x16x32_bf16 v[88:91], v[164:167], v[180:183], v[88:91]
	s_movk_i32 s2, 0x780
	s_mov_b32 s97, 0xf0000
	v_add3_u32 v134, v148, v151, s75
	ds_read_b128 v[128:131], v134 offset:14336
	ds_read_b128 v[136:139], v134 offset:12288
	ds_read_b128 v[140:143], v134 offset:10240
	ds_read_b128 v[144:147], v134 offset:8192
	ds_read_b128 v[152:155], v134 offset:6144
	ds_read_b128 v[156:159], v134 offset:4096
	ds_read_b128 v[160:163], v134 offset:2048
	ds_read_b128 v[164:167], v134
	v_add3_u32 v134, v150, v151, s63
	ds_read_b128 v[168:171], v134 offset:6144
	ds_read_b128 v[172:175], v134 offset:4096
	ds_read_b128 v[176:179], v134 offset:2048
	ds_read_b128 v[180:183], v134
	s_waitcnt lgkmcnt(0)
	v_mfma_f32_16x16x32_bf16 v[124:127], v[164:167], v[180:183], v[124:127]
	v_mfma_f32_16x16x32_bf16 v[120:123], v[164:167], v[176:179], v[120:123]
	v_mfma_f32_16x16x32_bf16 v[116:119], v[164:167], v[172:175], v[116:119]
	v_mfma_f32_16x16x32_bf16 v[112:115], v[164:167], v[168:171], v[112:115]
	v_mfma_f32_16x16x32_bf16 v[108:111], v[160:163], v[180:183], v[108:111]
	v_mfma_f32_16x16x32_bf16 v[104:107], v[160:163], v[176:179], v[104:107]
	v_mfma_f32_16x16x32_bf16 v[100:103], v[160:163], v[172:175], v[100:103]
	v_mfma_f32_16x16x32_bf16 v[96:99], v[160:163], v[168:171], v[96:99]
	v_mfma_f32_16x16x32_bf16 v[92:95], v[156:159], v[180:183], v[92:95]
	v_mfma_f32_16x16x32_bf16 v[84:87], v[156:159], v[176:179], v[84:87]
	v_mfma_f32_16x16x32_bf16 v[80:83], v[156:159], v[172:175], v[80:83]
	v_mfma_f32_16x16x32_bf16 v[76:79], v[156:159], v[168:171], v[76:79]
	v_mfma_f32_16x16x32_bf16 v[72:75], v[152:155], v[180:183], v[72:75]
	v_mfma_f32_16x16x32_bf16 v[68:71], v[152:155], v[176:179], v[68:71]
	v_mfma_f32_16x16x32_bf16 v[64:67], v[152:155], v[172:175], v[64:67]
	v_mfma_f32_16x16x32_bf16 v[60:63], v[152:155], v[168:171], v[60:63]
	v_add3_u32 v134, v150, v149, s63
	ds_read_b128 v[150:153], v134
	ds_read_b128 v[154:157], v134 offset:2048
	ds_read_b128 v[158:161], v134 offset:4096
	ds_read_b128 v[162:165], v134 offset:6144
	v_add3_u32 v134, v148, v149, s75
	ds_read_b128 v[198:201], v134
	ds_read_b128 v[202:205], v134 offset:2048
	ds_read_b128 v[206:209], v134 offset:4096
	ds_read_b128 v[210:213], v134 offset:6144
	v_mfma_f32_16x16x32_bf16 v[44:47], v[144:147], v[168:171], v[44:47]
	v_mfma_f32_16x16x32_bf16 v[40:43], v[140:143], v[180:183], v[40:43]
	v_mfma_f32_16x16x32_bf16 v[28:31], v[140:143], v[168:171], v[28:31]
	v_mfma_f32_16x16x32_bf16 v[24:27], v[136:139], v[180:183], v[24:27]
	v_mfma_f32_16x16x32_bf16 v[20:23], v[136:139], v[176:179], v[20:23]
	v_mfma_f32_16x16x32_bf16 v[16:19], v[136:139], v[172:175], v[16:19]
	v_mfma_f32_16x16x32_bf16 v[12:15], v[136:139], v[168:171], v[12:15]
	v_mfma_f32_16x16x32_bf16 v[8:11], v[128:131], v[180:183], v[8:11]
	v_mfma_f32_16x16x32_bf16 v[4:7], v[128:131], v[176:179], v[4:7]
	v_mfma_f32_16x16x32_bf16 v[0:3], v[128:131], v[172:175], v[0:3]
	v_mfma_f32_16x16x32_bf16 v[56:59], v[144:147], v[180:183], v[56:59]
	v_mfma_f32_16x16x32_bf16 v[52:55], v[144:147], v[176:179], v[52:55]
	v_mfma_f32_16x16x32_bf16 v[48:51], v[144:147], v[172:175], v[48:51]
	v_mfma_f32_16x16x32_bf16 v[36:39], v[140:143], v[176:179], v[36:39]
	v_mfma_f32_16x16x32_bf16 v[32:35], v[140:143], v[172:175], v[32:35]
	v_mfma_f32_16x16x32_bf16 v[88:91], v[128:131], v[168:171], v[88:91]
	ds_read_b128 v[128:131], v134 offset:8192
	ds_read_b128 v[136:139], v134 offset:10240
	ds_read_b128 v[140:143], v134 offset:12288
	ds_read_b128 v[144:147], v134 offset:14336
	s_waitcnt lgkmcnt(0)
	v_mfma_f32_16x16x32_bf16 v[124:127], v[198:201], v[150:153], v[124:127]
	v_mfma_f32_16x16x32_bf16 v[120:123], v[198:201], v[154:157], v[120:123]
	v_mfma_f32_16x16x32_bf16 v[116:119], v[198:201], v[158:161], v[116:119]
	v_mfma_f32_16x16x32_bf16 v[112:115], v[198:201], v[162:165], v[112:115]
	v_mfma_f32_16x16x32_bf16 v[108:111], v[202:205], v[150:153], v[108:111]
	v_mfma_f32_16x16x32_bf16 v[104:107], v[202:205], v[154:157], v[104:107]
	v_mfma_f32_16x16x32_bf16 v[100:103], v[202:205], v[158:161], v[100:103]
	v_mfma_f32_16x16x32_bf16 v[96:99], v[202:205], v[162:165], v[96:99]
	v_mfma_f32_16x16x32_bf16 v[92:95], v[206:209], v[150:153], v[92:95]
	v_mfma_f32_16x16x32_bf16 v[84:87], v[206:209], v[154:157], v[84:87]
	v_mfma_f32_16x16x32_bf16 v[80:83], v[206:209], v[158:161], v[80:83]
	v_mfma_f32_16x16x32_bf16 v[76:79], v[206:209], v[162:165], v[76:79]
	v_mfma_f32_16x16x32_bf16 v[72:75], v[210:213], v[150:153], v[72:75]
	v_mfma_f32_16x16x32_bf16 v[68:71], v[210:213], v[154:157], v[68:71]
	v_mfma_f32_16x16x32_bf16 v[64:67], v[210:213], v[158:161], v[64:67]
	v_mfma_f32_16x16x32_bf16 v[60:63], v[210:213], v[162:165], v[60:63]
	v_mov_b32_e32 v148, v184
	v_mfma_f32_16x16x32_bf16 v[24:27], v[140:143], v[150:153], v[24:27]
	s_waitcnt lgkmcnt(0)
	s_barrier
	v_mfma_f32_16x16x32_bf16 v[8:11], v[144:147], v[150:153], v[8:11]
	s_nop 5
	v_cvt_pk_bf16_f32 v24, v24, v25
	v_lshrrev_b32_e32 v134, 8, v148
	v_mul_i32_i24_e32 v134, 0x11000, v134
	v_lshrrev_b32_e32 v166, 1, v148
	v_and_b32_e32 v149, 0xcf, v148
	v_and_or_b32 v134, v166, 24, v134
	v_mfma_f32_16x16x32_bf16 v[56:59], v[128:131], v[150:153], v[56:59]
	v_cvt_pk_bf16_f32 v25, v26, v27
	v_cvt_pk_bf16_f32 v8, v8, v9
	v_cvt_pk_bf16_f32 v9, v10, v11
	v_mfma_f32_16x16x32_bf16 v[52:55], v[128:131], v[154:157], v[52:55]
	s_mov_b64 s[2:3], 0x2c00
	s_nop 2
	v_cvt_pk_bf16_f32 v56, v56, v57
	v_cvt_pk_bf16_f32 v57, v58, v59
	v_mfma_f32_16x16x32_bf16 v[48:51], v[128:131], v[158:161], v[48:51]
	v_cvt_pk_bf16_f32 v124, v124, v125
	v_cvt_pk_bf16_f32 v125, v126, v127
	v_cvt_pk_bf16_f32 v108, v108, v109
	v_mfma_f32_16x16x32_bf16 v[44:47], v[128:131], v[162:165], v[44:47]
	v_mad_u32_u24 v128, v149, s51, v134
	ds_write2_b64 v128, v[24:25], v[8:9] offset0:24 offset1:28
	v_cvt_pk_bf16_f32 v24, v52, v53
	v_mfma_f32_16x16x32_bf16 v[40:43], v[136:139], v[150:153], v[40:43]
	v_cvt_pk_bf16_f32 v25, v54, v55
	v_cvt_pk_bf16_f32 v109, v110, v111
	v_cvt_pk_bf16_f32 v92, v92, v93
	v_mfma_f32_16x16x32_bf16 v[8:11], v[140:143], v[154:157], v[20:23]
	v_cvt_pk_bf16_f32 v93, v94, v95
	s_nop 2
	v_cvt_pk_bf16_f32 v40, v40, v41
	v_cvt_pk_bf16_f32 v41, v42, v43
	v_mfma_f32_16x16x32_bf16 v[4:7], v[144:147], v[154:157], v[4:7]
	ds_write2_b64 v128, v[56:57], v[40:41] offset0:16 offset1:20
	v_add_u32_e32 v40, 0x1000, v128
	v_cvt_pk_bf16_f32 v8, v8, v9
	v_mfma_f32_16x16x32_bf16 v[32:35], v[136:139], v[158:161], v[32:35]
	v_cvt_pk_bf16_f32 v9, v10, v11
	s_nop 2
	v_cvt_pk_bf16_f32 v4, v4, v5
	v_cvt_pk_bf16_f32 v5, v6, v7
	v_mfma_f32_16x16x32_bf16 v[16:19], v[140:143], v[158:161], v[16:19]
	ds_write2_b64 v40, v[8:9], v[4:5] offset0:56 offset1:60
	v_cvt_pk_bf16_f32 v4, v116, v117
	v_cvt_pk_bf16_f32 v5, v118, v119
	v_mfma_f32_16x16x32_bf16 v[0:3], v[144:147], v[158:161], v[0:3]
	v_cvt_pk_bf16_f32 v6, v100, v101
	v_cvt_pk_bf16_f32 v7, v102, v103
	v_add_u32_e32 v8, 0x2000, v128
	v_cvt_pk_bf16_f32 v20, v120, v121
	v_cvt_pk_bf16_f32 v21, v122, v123
	v_cvt_pk_bf16_f32 v22, v104, v105
	v_cvt_pk_bf16_f32 v23, v106, v107
	ds_write2_b64 v8, v[4:5], v[6:7] offset0:64 offset1:68
	v_cvt_pk_bf16_f32 v4, v80, v81
	v_cvt_pk_bf16_f32 v5, v82, v83
	v_cvt_pk_bf16_f32 v6, v64, v65
	v_cvt_pk_bf16_f32 v7, v66, v67
	v_mfma_f32_16x16x32_bf16 v[28:31], v[136:139], v[162:165], v[28:31]
	ds_write2_b64 v40, v[20:21], v[22:23] offset0:32 offset1:36
	v_cvt_pk_bf16_f32 v20, v84, v85
	v_cvt_pk_bf16_f32 v21, v86, v87
	v_cvt_pk_bf16_f32 v22, v68, v69
	v_cvt_pk_bf16_f32 v23, v70, v71
	ds_write2_b64 v8, v[4:5], v[6:7] offset0:72 offset1:76
	v_cvt_pk_bf16_f32 v4, v48, v49
	v_cvt_pk_bf16_f32 v5, v50, v51
	v_cvt_pk_bf16_f32 v6, v32, v33
	v_cvt_pk_bf16_f32 v7, v34, v35
	v_mfma_f32_16x16x32_bf16 v[12:15], v[140:143], v[162:165], v[12:15]
	ds_write2_b64 v40, v[20:21], v[22:23] offset0:40 offset1:44
	ds_write2_b64 v8, v[4:5], v[6:7] offset0:80 offset1:84
	v_cvt_pk_bf16_f32 v4, v16, v17
	v_mfma_f32_16x16x32_bf16 v[20:23], v[144:147], v[162:165], v[88:91]
	v_cvt_pk_bf16_f32 v5, v18, v19
	v_cvt_pk_bf16_f32 v0, v0, v1
	v_cvt_pk_bf16_f32 v1, v2, v3
	ds_write2_b64 v8, v[4:5], v[0:1] offset0:88 offset1:92
	v_cvt_pk_bf16_f32 v0, v112, v113
	v_cvt_pk_bf16_f32 v1, v114, v115
	v_cvt_pk_bf16_f32 v2, v96, v97
	v_cvt_pk_bf16_f32 v3, v98, v99
	v_add_u32_e32 v4, 0x3000, v128
	ds_write2_b64 v4, v[0:1], v[2:3] offset0:96 offset1:100
	v_cvt_pk_bf16_f32 v0, v76, v77
	v_cvt_pk_bf16_f32 v1, v78, v79
	v_cvt_pk_bf16_f32 v2, v60, v61
	v_cvt_pk_bf16_f32 v3, v62, v63
	v_mfma_f32_16x16x32_bf16 v[36:39], v[136:139], v[154:157], v[36:39]
	ds_write2_b64 v4, v[0:1], v[2:3] offset0:104 offset1:108
	v_cvt_pk_bf16_f32 v0, v44, v45
	v_cvt_pk_bf16_f32 v1, v46, v47
	v_cvt_pk_bf16_f32 v2, v28, v29
	v_cvt_pk_bf16_f32 v3, v30, v31
	ds_write2_b64 v4, v[0:1], v[2:3] offset0:112 offset1:116
	v_cvt_pk_bf16_f32 v0, v12, v13
	v_cvt_pk_bf16_f32 v1, v14, v15
	v_cvt_pk_bf16_f32 v2, v20, v21
	v_cvt_pk_bf16_f32 v3, v22, v23
	ds_write2_b64 v4, v[0:1], v[2:3] offset0:120 offset1:124
	v_lshlrev_b32_e32 v0, 3, v148
	v_and_b32_e32 v32, 0x78, v0
	v_cvt_pk_bf16_f32 v26, v36, v37
	v_cvt_pk_bf16_f32 v27, v38, v39
	v_lshl_or_b32 v134, s44, 7, v32
	ds_write2_b64 v40, v[24:25], v[26:27] offset0:48 offset1:52
	v_lshlrev_b64 v[24:25], 2, v[134:135]
	v_lshl_add_u64 v[16:17], s[10:11], 0, v[24:25]
	v_cvt_pk_bf16_f32 v72, v72, v73
	v_cvt_pk_bf16_f32 v73, v74, v75
	v_lshl_add_u64 v[12:13], v[16:17], 0, s[2:3]
	s_movk_i32 s2, 0x2000
	ds_write2_b64 v128, v[124:125], v[108:109] offset1:4
	ds_write2_b64 v128, v[92:93], v[72:73] offset0:8 offset1:12
	v_add_co_u32_e32 v8, vcc, s2, v16
	s_mov_b64 s[2:3], 0x5800
	s_waitcnt lgkmcnt(0)
	s_barrier
	v_addc_co_u32_e32 v9, vcc, 0, v17, vcc
	v_lshl_add_u64 v[20:21], v[16:17], 0, s[2:3]
	s_movk_i32 s2, 0x5000
	v_add_co_u32_e32 v16, vcc, s2, v16
	v_lshl_add_u64 v[28:29], s[12:13], 0, v[24:25]
	s_nop 0
	v_addc_co_u32_e32 v17, vcc, 0, v17, vcc
	s_nop 0
	s_nop 0
	s_nop 0
	s_nop 0
	s_nop 0
	v_ashrrev_i32_e32 v33, 4, v148
	v_mul_lo_u32 v34, v33, s51
	s_mov_b32 s44, 0
	v_lshl_add_u64 v[40:41], v[134:135], 1, s[22:23]
	v_lshl_add_u32 v44, v32, 1, v34
	v_add_u32_e32 v45, 31, v33
	s_waitcnt vmcnt(0)
	s_add_i32 s2, s92, 0xff
	s_ashr_i32 s2, s2, 12
	s_ashr_i32 s3, s92, 12
	s_cmp_eq_u32 s2, s3
	s_cbranch_scc0 .LBB0_2308
	s_mov_b32 s98, 0x3e6d3388
	s_mov_b32 s100, 0xbf38aa3b
	s_mov_b32 s2, s35
	s_mov_b32 s3, 0
	v_mov_b64_e32 v[180:181], s[76:77]
	v_lshlrev_b32_e32 v212, 1, v32
	v_lshl_add_u32 v126, v34, 3, v212
	v_add_u32_e32 v127, 0x11000, v126
	v_subrev_u32_e32 v182, 0x110, v126
	v_max_i32_e32 v182, v182, v212
	v_mov_b32_e32 v183, v33
	v_lshl_add_u32 v212, v33, 3, s36
	v_add_u32_e32 v212, -1, v212
	v_mad_i64_i32 v[124:125], s[94:95], v212, s35, v[40:41]
	ds_read_b128 v[0:3], v182
	ds_read_b128 v[4:7], v126
	ds_read_b128 v[8:11], v126 offset:272
	ds_read_b128 v[50:53], v127
	ds_read_b128 v[12:15], v126 offset:544
	ds_read_b128 v[54:57], v127 offset:272
	ds_read_b128 v[16:19], v126 offset:816
	ds_read_b128 v[58:61], v127 offset:544
	ds_read_b128 v[20:23], v126 offset:1088
	ds_read_b128 v[62:65], v127 offset:816
	ds_read_b128 v[24:27], v126 offset:1360
	ds_read_b128 v[66:69], v127 offset:1088
	ds_read_b128 v[28:31], v126 offset:1632
	ds_read_b128 v[70:73], v127 offset:1360
	ds_read_b128 v[32:35], v126 offset:1904
	ds_read_b128 v[74:77], v127 offset:1632
	ds_read_b128 v[36:39], v126 offset:2176
	ds_read_b128 v[78:81], v127 offset:1904
	s_waitcnt lgkmcnt(15)
	v_lshlrev_b32_e32 v82, 16, v0
	v_and_b32_e32 v83, 0xffff0000, v0
	v_lshlrev_b32_e32 v84, 16, v1
	v_and_b32_e32 v85, 0xffff0000, v1
	v_lshlrev_b32_e32 v86, 16, v2
	v_and_b32_e32 v87, 0xffff0000, v2
	v_lshlrev_b32_e32 v88, 16, v3
	v_and_b32_e32 v89, 0xffff0000, v3
	v_lshlrev_b32_e32 v90, 16, v4
	v_and_b32_e32 v91, 0xffff0000, v4
	v_lshlrev_b32_e32 v92, 16, v5
	v_and_b32_e32 v93, 0xffff0000, v5
	v_lshlrev_b32_e32 v94, 16, v6
	v_and_b32_e32 v95, 0xffff0000, v6
	v_lshlrev_b32_e32 v96, 16, v7
	v_and_b32_e32 v97, 0xffff0000, v7
	s_waitcnt lgkmcnt(14)
	v_lshlrev_b32_e32 v98, 16, v8
	v_and_b32_e32 v99, 0xffff0000, v8
	v_lshlrev_b32_e32 v100, 16, v9
	v_and_b32_e32 v101, 0xffff0000, v9
	v_lshlrev_b32_e32 v102, 16, v10
	v_and_b32_e32 v103, 0xffff0000, v10
	v_lshlrev_b32_e32 v104, 16, v11
	v_and_b32_e32 v105, 0xffff0000, v11
	v_pk_fma_f32 v[106:107], v[234:235], v[82:83], v[218:219]
	v_pk_fma_f32 v[152:153], v[236:237], v[84:85], v[220:221]
	v_pk_fma_f32 v[166:167], v[230:231], v[86:87], v[214:215]
	v_pk_fma_f32 v[198:199], v[232:233], v[88:89], v[216:217]
	v_pk_fma_f32 v[106:107], v[238:239], v[90:91], v[106:107]
	v_pk_fma_f32 v[152:153], v[240:241], v[92:93], v[152:153]
	v_pk_fma_f32 v[166:167], v[242:243], v[94:95], v[166:167]
	v_pk_fma_f32 v[198:199], v[244:245], v[96:97], v[198:199]
	v_pk_fma_f32 v[106:107], v[246:247], v[98:99], v[106:107]
	v_pk_fma_f32 v[152:153], v[248:249], v[100:101], v[152:153]
	v_pk_fma_f32 v[166:167], v[250:251], v[102:103], v[166:167]
	v_pk_fma_f32 v[198:199], v[252:253], v[104:105], v[198:199]
	v_fma_f32 v108, |v106|, s98, 1.0
	v_fma_f32 v109, |v107|, s98, 1.0
	v_fma_f32 v154, |v152|, s98, 1.0
	v_fma_f32 v155, |v153|, s98, 1.0
	v_fma_f32 v168, |v166|, s98, 1.0
	v_fma_f32 v169, |v167|, s98, 1.0
	v_fma_f32 v200, |v198|, s98, 1.0
	v_fma_f32 v201, |v199|, s98, 1.0
	v_mul_f32_e32 v110, v108, v109
	v_mul_f32_e32 v156, v154, v155
	v_mul_f32_e32 v170, v168, v169
	v_mul_f32_e32 v202, v200, v201
	v_pk_mul_f32 v[112:113], v[106:107], v[106:107]
	v_pk_mul_f32 v[158:159], v[152:153], v[152:153]
	v_pk_mul_f32 v[172:173], v[166:167], v[166:167]
	v_pk_mul_f32 v[204:205], v[198:199], v[198:199]
	v_rcp_f32_e32 v110, v110
	v_rcp_f32_e32 v156, v156
	v_rcp_f32_e32 v170, v170
	v_rcp_f32_e32 v202, v202
	v_pk_mul_f32 v[112:113], v[112:113], s[100:101] op_sel_hi:[1,0]
	v_pk_mul_f32 v[158:159], v[158:159], s[100:101] op_sel_hi:[1,0]
	v_pk_mul_f32 v[172:173], v[172:173], s[100:101] op_sel_hi:[1,0]
	v_pk_mul_f32 v[204:205], v[204:205], s[100:101] op_sel_hi:[1,0]
	v_pk_mul_f32 v[108:109], v[108:109], v[110:111] op_sel:[1,0] op_sel_hi:[0,0]
	v_pk_mul_f32 v[154:155], v[154:155], v[156:157] op_sel:[1,0] op_sel_hi:[0,0]
	v_pk_mul_f32 v[168:169], v[168:169], v[170:171] op_sel:[1,0] op_sel_hi:[0,0]
	v_pk_mul_f32 v[200:201], v[200:201], v[202:203] op_sel:[1,0] op_sel_hi:[0,0]
	v_exp_f32_e32 v112, v112
	v_exp_f32_e32 v113, v113
	v_exp_f32_e32 v158, v158
	v_exp_f32_e32 v159, v159
	v_exp_f32_e32 v172, v172
	v_exp_f32_e32 v173, v173
	v_exp_f32_e32 v204, v204
	v_exp_f32_e32 v205, v205
	v_pk_fma_f32 v[114:115], v[108:109], s[74:75], v[180:181] op_sel_hi:[1,0,0]
	v_pk_fma_f32 v[160:161], v[154:155], s[74:75], v[180:181] op_sel_hi:[1,0,0]
	v_pk_fma_f32 v[174:175], v[168:169], s[74:75], v[180:181] op_sel_hi:[1,0,0]
	v_pk_fma_f32 v[206:207], v[200:201], s[74:75], v[180:181] op_sel_hi:[1,0,0]
	v_pk_fma_f32 v[114:115], v[108:109], v[114:115], s[78:79] op_sel_hi:[1,1,0]
	v_pk_fma_f32 v[160:161], v[154:155], v[160:161], s[78:79] op_sel_hi:[1,1,0]
	v_pk_fma_f32 v[174:175], v[168:169], v[174:175], s[78:79] op_sel_hi:[1,1,0]
	v_pk_fma_f32 v[206:207], v[200:201], v[206:207], s[78:79] op_sel_hi:[1,1,0]
	v_pk_fma_f32 v[114:115], v[108:109], v[114:115], s[80:81] op_sel_hi:[1,1,0]
	v_pk_fma_f32 v[160:161], v[154:155], v[160:161], s[80:81] op_sel_hi:[1,1,0]
	v_pk_fma_f32 v[174:175], v[168:169], v[174:175], s[80:81] op_sel_hi:[1,1,0]
	v_pk_fma_f32 v[206:207], v[200:201], v[206:207], s[80:81] op_sel_hi:[1,1,0]
	v_pk_fma_f32 v[114:115], v[108:109], v[114:115], s[82:83] op_sel_hi:[1,1,0]
	v_pk_fma_f32 v[160:161], v[154:155], v[160:161], s[82:83] op_sel_hi:[1,1,0]
	v_pk_fma_f32 v[174:175], v[168:169], v[174:175], s[82:83] op_sel_hi:[1,1,0]
	v_pk_fma_f32 v[206:207], v[200:201], v[206:207], s[82:83] op_sel_hi:[1,1,0]
	v_pk_mul_f32 v[114:115], v[108:109], v[114:115]
	v_pk_mul_f32 v[160:161], v[154:155], v[160:161]
	v_pk_mul_f32 v[174:175], v[168:169], v[174:175]
	v_pk_mul_f32 v[206:207], v[200:201], v[206:207]
	v_pk_fma_f32 v[112:113], v[112:113], v[114:115], 1.0 op_sel_hi:[1,1,0] neg_lo:[1,0,0] neg_hi:[1,0,0]
	v_pk_fma_f32 v[158:159], v[158:159], v[160:161], 1.0 op_sel_hi:[1,1,0] neg_lo:[1,0,0] neg_hi:[1,0,0]
	v_pk_fma_f32 v[172:173], v[172:173], v[174:175], 1.0 op_sel_hi:[1,1,0] neg_lo:[1,0,0] neg_hi:[1,0,0]
	v_pk_fma_f32 v[204:205], v[204:205], v[206:207], 1.0 op_sel_hi:[1,1,0] neg_lo:[1,0,0] neg_hi:[1,0,0]
	v_bfi_b32 v113, s34, v113, v107
	v_bfi_b32 v112, s34, v112, v106
	v_bfi_b32 v159, s34, v159, v153
	v_bfi_b32 v158, s34, v158, v152
	v_bfi_b32 v173, s34, v173, v167
	v_bfi_b32 v172, s34, v172, v166
	v_bfi_b32 v205, s34, v205, v199
	v_bfi_b32 v204, s34, v204, v198
	v_pk_mul_f32 v[116:117], v[106:107], 0.5 op_sel_hi:[1,0]
	v_pk_mul_f32 v[162:163], v[152:153], 0.5 op_sel_hi:[1,0]
	v_pk_mul_f32 v[176:177], v[166:167], 0.5 op_sel_hi:[1,0]
	v_pk_mul_f32 v[208:209], v[198:199], 0.5 op_sel_hi:[1,0]
	v_lshlrev_b32_e32 v118, 16, v50
	v_and_b32_e32 v119, 0xffff0000, v50
	v_lshlrev_b32_e32 v164, 16, v51
	v_and_b32_e32 v165, 0xffff0000, v51
	v_lshlrev_b32_e32 v178, 16, v52
	v_and_b32_e32 v179, 0xffff0000, v52
	v_lshlrev_b32_e32 v210, 16, v53
	v_and_b32_e32 v211, 0xffff0000, v53
	v_pk_fma_f32 v[116:117], v[116:117], v[112:113], v[116:117]
	v_pk_fma_f32 v[162:163], v[162:163], v[158:159], v[162:163]
	v_pk_fma_f32 v[176:177], v[176:177], v[172:173], v[176:177]
	v_pk_fma_f32 v[208:209], v[208:209], v[204:205], v[208:209]
	v_pk_mul_f32 v[116:117], v[116:117], v[118:119]
	v_pk_mul_f32 v[162:163], v[162:163], v[164:165]
	v_pk_mul_f32 v[176:177], v[176:177], v[178:179]
	v_pk_mul_f32 v[208:209], v[208:209], v[210:211]
	v_cvt_pk_bf16_f32 v120, v116, v117
	v_cvt_pk_bf16_f32 v121, v162, v163
	v_cvt_pk_bf16_f32 v122, v176, v177
	v_cvt_pk_bf16_f32 v123, v208, v209
	v_cmp_ne_u32_e32 vcc, 0, v183
	s_and_saveexec_b64 s[94:95], vcc
	global_store_dwordx4 v[124:125], v[120:123], off nt
	s_mov_b64 exec, s[94:95]
	v_lshl_add_u64 v[124:125], v[124:125], 0, s[2:3]
	s_waitcnt lgkmcnt(12)
	v_lshlrev_b32_e32 v82, 16, v12
	v_and_b32_e32 v83, 0xffff0000, v12
	v_lshlrev_b32_e32 v84, 16, v13
	v_and_b32_e32 v85, 0xffff0000, v13
	v_lshlrev_b32_e32 v86, 16, v14
	v_and_b32_e32 v87, 0xffff0000, v14
	v_lshlrev_b32_e32 v88, 16, v15
	v_and_b32_e32 v89, 0xffff0000, v15
	v_pk_fma_f32 v[106:107], v[234:235], v[90:91], v[218:219]
	v_pk_fma_f32 v[152:153], v[236:237], v[92:93], v[220:221]
	v_pk_fma_f32 v[166:167], v[230:231], v[94:95], v[214:215]
	v_pk_fma_f32 v[198:199], v[232:233], v[96:97], v[216:217]
	v_pk_fma_f32 v[106:107], v[238:239], v[98:99], v[106:107]
	v_pk_fma_f32 v[152:153], v[240:241], v[100:101], v[152:153]
	v_pk_fma_f32 v[166:167], v[242:243], v[102:103], v[166:167]
	v_pk_fma_f32 v[198:199], v[244:245], v[104:105], v[198:199]
	v_pk_fma_f32 v[106:107], v[246:247], v[82:83], v[106:107]
	v_pk_fma_f32 v[152:153], v[248:249], v[84:85], v[152:153]
	v_pk_fma_f32 v[166:167], v[250:251], v[86:87], v[166:167]
	v_pk_fma_f32 v[198:199], v[252:253], v[88:89], v[198:199]
	v_fma_f32 v108, |v106|, s98, 1.0
	v_fma_f32 v109, |v107|, s98, 1.0
	v_fma_f32 v154, |v152|, s98, 1.0
	v_fma_f32 v155, |v153|, s98, 1.0
	v_fma_f32 v168, |v166|, s98, 1.0
	v_fma_f32 v169, |v167|, s98, 1.0
	v_fma_f32 v200, |v198|, s98, 1.0
	v_fma_f32 v201, |v199|, s98, 1.0
	v_mul_f32_e32 v110, v108, v109
	v_mul_f32_e32 v156, v154, v155
	v_mul_f32_e32 v170, v168, v169
	v_mul_f32_e32 v202, v200, v201
	v_pk_mul_f32 v[112:113], v[106:107], v[106:107]
	v_pk_mul_f32 v[158:159], v[152:153], v[152:153]
	v_pk_mul_f32 v[172:173], v[166:167], v[166:167]
	v_pk_mul_f32 v[204:205], v[198:199], v[198:199]
	v_rcp_f32_e32 v110, v110
	v_rcp_f32_e32 v156, v156
	v_rcp_f32_e32 v170, v170
	v_rcp_f32_e32 v202, v202
	v_pk_mul_f32 v[112:113], v[112:113], s[100:101] op_sel_hi:[1,0]
	v_pk_mul_f32 v[158:159], v[158:159], s[100:101] op_sel_hi:[1,0]
	v_pk_mul_f32 v[172:173], v[172:173], s[100:101] op_sel_hi:[1,0]
	v_pk_mul_f32 v[204:205], v[204:205], s[100:101] op_sel_hi:[1,0]
	v_pk_mul_f32 v[108:109], v[108:109], v[110:111] op_sel:[1,0] op_sel_hi:[0,0]
	v_pk_mul_f32 v[154:155], v[154:155], v[156:157] op_sel:[1,0] op_sel_hi:[0,0]
	v_pk_mul_f32 v[168:169], v[168:169], v[170:171] op_sel:[1,0] op_sel_hi:[0,0]
	v_pk_mul_f32 v[200:201], v[200:201], v[202:203] op_sel:[1,0] op_sel_hi:[0,0]
	v_exp_f32_e32 v112, v112
	v_exp_f32_e32 v113, v113
	v_exp_f32_e32 v158, v158
	v_exp_f32_e32 v159, v159
	v_exp_f32_e32 v172, v172
	v_exp_f32_e32 v173, v173
	v_exp_f32_e32 v204, v204
	v_exp_f32_e32 v205, v205
	v_pk_fma_f32 v[114:115], v[108:109], s[74:75], v[180:181] op_sel_hi:[1,0,0]
	v_pk_fma_f32 v[160:161], v[154:155], s[74:75], v[180:181] op_sel_hi:[1,0,0]
	v_pk_fma_f32 v[174:175], v[168:169], s[74:75], v[180:181] op_sel_hi:[1,0,0]
	v_pk_fma_f32 v[206:207], v[200:201], s[74:75], v[180:181] op_sel_hi:[1,0,0]
	v_pk_fma_f32 v[114:115], v[108:109], v[114:115], s[78:79] op_sel_hi:[1,1,0]
	v_pk_fma_f32 v[160:161], v[154:155], v[160:161], s[78:79] op_sel_hi:[1,1,0]
	v_pk_fma_f32 v[174:175], v[168:169], v[174:175], s[78:79] op_sel_hi:[1,1,0]
	v_pk_fma_f32 v[206:207], v[200:201], v[206:207], s[78:79] op_sel_hi:[1,1,0]
	v_pk_fma_f32 v[114:115], v[108:109], v[114:115], s[80:81] op_sel_hi:[1,1,0]
	v_pk_fma_f32 v[160:161], v[154:155], v[160:161], s[80:81] op_sel_hi:[1,1,0]
	v_pk_fma_f32 v[174:175], v[168:169], v[174:175], s[80:81] op_sel_hi:[1,1,0]
	v_pk_fma_f32 v[206:207], v[200:201], v[206:207], s[80:81] op_sel_hi:[1,1,0]
	v_pk_fma_f32 v[114:115], v[108:109], v[114:115], s[82:83] op_sel_hi:[1,1,0]
	v_pk_fma_f32 v[160:161], v[154:155], v[160:161], s[82:83] op_sel_hi:[1,1,0]
	v_pk_fma_f32 v[174:175], v[168:169], v[174:175], s[82:83] op_sel_hi:[1,1,0]
	v_pk_fma_f32 v[206:207], v[200:201], v[206:207], s[82:83] op_sel_hi:[1,1,0]
	v_pk_mul_f32 v[114:115], v[108:109], v[114:115]
	v_pk_mul_f32 v[160:161], v[154:155], v[160:161]
	v_pk_mul_f32 v[174:175], v[168:169], v[174:175]
	v_pk_mul_f32 v[206:207], v[200:201], v[206:207]
	v_pk_fma_f32 v[112:113], v[112:113], v[114:115], 1.0 op_sel_hi:[1,1,0] neg_lo:[1,0,0] neg_hi:[1,0,0]
	v_pk_fma_f32 v[158:159], v[158:159], v[160:161], 1.0 op_sel_hi:[1,1,0] neg_lo:[1,0,0] neg_hi:[1,0,0]
	v_pk_fma_f32 v[172:173], v[172:173], v[174:175], 1.0 op_sel_hi:[1,1,0] neg_lo:[1,0,0] neg_hi:[1,0,0]
	v_pk_fma_f32 v[204:205], v[204:205], v[206:207], 1.0 op_sel_hi:[1,1,0] neg_lo:[1,0,0] neg_hi:[1,0,0]
	v_bfi_b32 v113, s34, v113, v107
	v_bfi_b32 v112, s34, v112, v106
	v_bfi_b32 v159, s34, v159, v153
	v_bfi_b32 v158, s34, v158, v152
	v_bfi_b32 v173, s34, v173, v167
	v_bfi_b32 v172, s34, v172, v166
	v_bfi_b32 v205, s34, v205, v199
	v_bfi_b32 v204, s34, v204, v198
	v_pk_mul_f32 v[116:117], v[106:107], 0.5 op_sel_hi:[1,0]
	v_pk_mul_f32 v[162:163], v[152:153], 0.5 op_sel_hi:[1,0]
	v_pk_mul_f32 v[176:177], v[166:167], 0.5 op_sel_hi:[1,0]
	v_pk_mul_f32 v[208:209], v[198:199], 0.5 op_sel_hi:[1,0]
	v_lshlrev_b32_e32 v118, 16, v54
	v_and_b32_e32 v119, 0xffff0000, v54
	v_lshlrev_b32_e32 v164, 16, v55
	v_and_b32_e32 v165, 0xffff0000, v55
	v_lshlrev_b32_e32 v178, 16, v56
	v_and_b32_e32 v179, 0xffff0000, v56
	v_lshlrev_b32_e32 v210, 16, v57
	v_and_b32_e32 v211, 0xffff0000, v57
	v_pk_fma_f32 v[116:117], v[116:117], v[112:113], v[116:117]
	v_pk_fma_f32 v[162:163], v[162:163], v[158:159], v[162:163]
	v_pk_fma_f32 v[176:177], v[176:177], v[172:173], v[176:177]
	v_pk_fma_f32 v[208:209], v[208:209], v[204:205], v[208:209]
	v_pk_mul_f32 v[116:117], v[116:117], v[118:119]
	v_pk_mul_f32 v[162:163], v[162:163], v[164:165]
	v_pk_mul_f32 v[176:177], v[176:177], v[178:179]
	v_pk_mul_f32 v[208:209], v[208:209], v[210:211]
	v_cvt_pk_bf16_f32 v120, v116, v117
	v_cvt_pk_bf16_f32 v121, v162, v163
	v_cvt_pk_bf16_f32 v122, v176, v177
	v_cvt_pk_bf16_f32 v123, v208, v209
	global_store_dwordx4 v[124:125], v[120:123], off nt
	v_lshl_add_u64 v[124:125], v[124:125], 0, s[2:3]
	s_waitcnt lgkmcnt(10)
	v_lshlrev_b32_e32 v90, 16, v16
	v_and_b32_e32 v91, 0xffff0000, v16
	v_lshlrev_b32_e32 v92, 16, v17
	v_and_b32_e32 v93, 0xffff0000, v17
	v_lshlrev_b32_e32 v94, 16, v18
	v_and_b32_e32 v95, 0xffff0000, v18
	v_lshlrev_b32_e32 v96, 16, v19
	v_and_b32_e32 v97, 0xffff0000, v19
	v_pk_fma_f32 v[106:107], v[234:235], v[98:99], v[218:219]
	v_pk_fma_f32 v[152:153], v[236:237], v[100:101], v[220:221]
	v_pk_fma_f32 v[166:167], v[230:231], v[102:103], v[214:215]
	v_pk_fma_f32 v[198:199], v[232:233], v[104:105], v[216:217]
	v_pk_fma_f32 v[106:107], v[238:239], v[82:83], v[106:107]
	v_pk_fma_f32 v[152:153], v[240:241], v[84:85], v[152:153]
	v_pk_fma_f32 v[166:167], v[242:243], v[86:87], v[166:167]
	v_pk_fma_f32 v[198:199], v[244:245], v[88:89], v[198:199]
	v_pk_fma_f32 v[106:107], v[246:247], v[90:91], v[106:107]
	v_pk_fma_f32 v[152:153], v[248:249], v[92:93], v[152:153]
	v_pk_fma_f32 v[166:167], v[250:251], v[94:95], v[166:167]
	v_pk_fma_f32 v[198:199], v[252:253], v[96:97], v[198:199]
	v_fma_f32 v108, |v106|, s98, 1.0
	v_fma_f32 v109, |v107|, s98, 1.0
	v_fma_f32 v154, |v152|, s98, 1.0
	v_fma_f32 v155, |v153|, s98, 1.0
	v_fma_f32 v168, |v166|, s98, 1.0
	v_fma_f32 v169, |v167|, s98, 1.0
	v_fma_f32 v200, |v198|, s98, 1.0
	v_fma_f32 v201, |v199|, s98, 1.0
	v_mul_f32_e32 v110, v108, v109
	v_mul_f32_e32 v156, v154, v155
	v_mul_f32_e32 v170, v168, v169
	v_mul_f32_e32 v202, v200, v201
	v_pk_mul_f32 v[112:113], v[106:107], v[106:107]
	v_pk_mul_f32 v[158:159], v[152:153], v[152:153]
	v_pk_mul_f32 v[172:173], v[166:167], v[166:167]
	v_pk_mul_f32 v[204:205], v[198:199], v[198:199]
	v_rcp_f32_e32 v110, v110
	v_rcp_f32_e32 v156, v156
	v_rcp_f32_e32 v170, v170
	v_rcp_f32_e32 v202, v202
	v_pk_mul_f32 v[112:113], v[112:113], s[100:101] op_sel_hi:[1,0]
	v_pk_mul_f32 v[158:159], v[158:159], s[100:101] op_sel_hi:[1,0]
	v_pk_mul_f32 v[172:173], v[172:173], s[100:101] op_sel_hi:[1,0]
	v_pk_mul_f32 v[204:205], v[204:205], s[100:101] op_sel_hi:[1,0]
	v_pk_mul_f32 v[108:109], v[108:109], v[110:111] op_sel:[1,0] op_sel_hi:[0,0]
	v_pk_mul_f32 v[154:155], v[154:155], v[156:157] op_sel:[1,0] op_sel_hi:[0,0]
	v_pk_mul_f32 v[168:169], v[168:169], v[170:171] op_sel:[1,0] op_sel_hi:[0,0]
	v_pk_mul_f32 v[200:201], v[200:201], v[202:203] op_sel:[1,0] op_sel_hi:[0,0]
	v_exp_f32_e32 v112, v112
	v_exp_f32_e32 v113, v113
	v_exp_f32_e32 v158, v158
	v_exp_f32_e32 v159, v159
	v_exp_f32_e32 v172, v172
	v_exp_f32_e32 v173, v173
	v_exp_f32_e32 v204, v204
	v_exp_f32_e32 v205, v205
	v_pk_fma_f32 v[114:115], v[108:109], s[74:75], v[180:181] op_sel_hi:[1,0,0]
	v_pk_fma_f32 v[160:161], v[154:155], s[74:75], v[180:181] op_sel_hi:[1,0,0]
	v_pk_fma_f32 v[174:175], v[168:169], s[74:75], v[180:181] op_sel_hi:[1,0,0]
	v_pk_fma_f32 v[206:207], v[200:201], s[74:75], v[180:181] op_sel_hi:[1,0,0]
	v_pk_fma_f32 v[114:115], v[108:109], v[114:115], s[78:79] op_sel_hi:[1,1,0]
	v_pk_fma_f32 v[160:161], v[154:155], v[160:161], s[78:79] op_sel_hi:[1,1,0]
	v_pk_fma_f32 v[174:175], v[168:169], v[174:175], s[78:79] op_sel_hi:[1,1,0]
	v_pk_fma_f32 v[206:207], v[200:201], v[206:207], s[78:79] op_sel_hi:[1,1,0]
	v_pk_fma_f32 v[114:115], v[108:109], v[114:115], s[80:81] op_sel_hi:[1,1,0]
	v_pk_fma_f32 v[160:161], v[154:155], v[160:161], s[80:81] op_sel_hi:[1,1,0]
	v_pk_fma_f32 v[174:175], v[168:169], v[174:175], s[80:81] op_sel_hi:[1,1,0]
	v_pk_fma_f32 v[206:207], v[200:201], v[206:207], s[80:81] op_sel_hi:[1,1,0]
	v_pk_fma_f32 v[114:115], v[108:109], v[114:115], s[82:83] op_sel_hi:[1,1,0]
	v_pk_fma_f32 v[160:161], v[154:155], v[160:161], s[82:83] op_sel_hi:[1,1,0]
	v_pk_fma_f32 v[174:175], v[168:169], v[174:175], s[82:83] op_sel_hi:[1,1,0]
	v_pk_fma_f32 v[206:207], v[200:201], v[206:207], s[82:83] op_sel_hi:[1,1,0]
	v_pk_mul_f32 v[114:115], v[108:109], v[114:115]
	v_pk_mul_f32 v[160:161], v[154:155], v[160:161]
	v_pk_mul_f32 v[174:175], v[168:169], v[174:175]
	v_pk_mul_f32 v[206:207], v[200:201], v[206:207]
	v_pk_fma_f32 v[112:113], v[112:113], v[114:115], 1.0 op_sel_hi:[1,1,0] neg_lo:[1,0,0] neg_hi:[1,0,0]
	v_pk_fma_f32 v[158:159], v[158:159], v[160:161], 1.0 op_sel_hi:[1,1,0] neg_lo:[1,0,0] neg_hi:[1,0,0]
	v_pk_fma_f32 v[172:173], v[172:173], v[174:175], 1.0 op_sel_hi:[1,1,0] neg_lo:[1,0,0] neg_hi:[1,0,0]
	v_pk_fma_f32 v[204:205], v[204:205], v[206:207], 1.0 op_sel_hi:[1,1,0] neg_lo:[1,0,0] neg_hi:[1,0,0]
	v_bfi_b32 v113, s34, v113, v107
	v_bfi_b32 v112, s34, v112, v106
	v_bfi_b32 v159, s34, v159, v153
	v_bfi_b32 v158, s34, v158, v152
	v_bfi_b32 v173, s34, v173, v167
	v_bfi_b32 v172, s34, v172, v166
	v_bfi_b32 v205, s34, v205, v199
	v_bfi_b32 v204, s34, v204, v198
	v_pk_mul_f32 v[116:117], v[106:107], 0.5 op_sel_hi:[1,0]
	v_pk_mul_f32 v[162:163], v[152:153], 0.5 op_sel_hi:[1,0]
	v_pk_mul_f32 v[176:177], v[166:167], 0.5 op_sel_hi:[1,0]
	v_pk_mul_f32 v[208:209], v[198:199], 0.5 op_sel_hi:[1,0]
	v_lshlrev_b32_e32 v118, 16, v58
	v_and_b32_e32 v119, 0xffff0000, v58
	v_lshlrev_b32_e32 v164, 16, v59
	v_and_b32_e32 v165, 0xffff0000, v59
	v_lshlrev_b32_e32 v178, 16, v60
	v_and_b32_e32 v179, 0xffff0000, v60
	v_lshlrev_b32_e32 v210, 16, v61
	v_and_b32_e32 v211, 0xffff0000, v61
	v_pk_fma_f32 v[116:117], v[116:117], v[112:113], v[116:117]
	v_pk_fma_f32 v[162:163], v[162:163], v[158:159], v[162:163]
	v_pk_fma_f32 v[176:177], v[176:177], v[172:173], v[176:177]
	v_pk_fma_f32 v[208:209], v[208:209], v[204:205], v[208:209]
	v_pk_mul_f32 v[116:117], v[116:117], v[118:119]
	v_pk_mul_f32 v[162:163], v[162:163], v[164:165]
	v_pk_mul_f32 v[176:177], v[176:177], v[178:179]
	v_pk_mul_f32 v[208:209], v[208:209], v[210:211]
	v_cvt_pk_bf16_f32 v120, v116, v117
	v_cvt_pk_bf16_f32 v121, v162, v163
	v_cvt_pk_bf16_f32 v122, v176, v177
	v_cvt_pk_bf16_f32 v123, v208, v209
	global_store_dwordx4 v[124:125], v[120:123], off nt
	v_lshl_add_u64 v[124:125], v[124:125], 0, s[2:3]
	s_waitcnt lgkmcnt(8)
	v_lshlrev_b32_e32 v98, 16, v20
	v_and_b32_e32 v99, 0xffff0000, v20
	v_lshlrev_b32_e32 v100, 16, v21
	v_and_b32_e32 v101, 0xffff0000, v21
	v_lshlrev_b32_e32 v102, 16, v22
	v_and_b32_e32 v103, 0xffff0000, v22
	v_lshlrev_b32_e32 v104, 16, v23
	v_and_b32_e32 v105, 0xffff0000, v23
	v_pk_fma_f32 v[106:107], v[234:235], v[82:83], v[218:219]
	v_pk_fma_f32 v[152:153], v[236:237], v[84:85], v[220:221]
	v_pk_fma_f32 v[166:167], v[230:231], v[86:87], v[214:215]
	v_pk_fma_f32 v[198:199], v[232:233], v[88:89], v[216:217]
	v_pk_fma_f32 v[106:107], v[238:239], v[90:91], v[106:107]
	v_pk_fma_f32 v[152:153], v[240:241], v[92:93], v[152:153]
	v_pk_fma_f32 v[166:167], v[242:243], v[94:95], v[166:167]
	v_pk_fma_f32 v[198:199], v[244:245], v[96:97], v[198:199]
	v_pk_fma_f32 v[106:107], v[246:247], v[98:99], v[106:107]
	v_pk_fma_f32 v[152:153], v[248:249], v[100:101], v[152:153]
	v_pk_fma_f32 v[166:167], v[250:251], v[102:103], v[166:167]
	v_pk_fma_f32 v[198:199], v[252:253], v[104:105], v[198:199]
	v_fma_f32 v108, |v106|, s98, 1.0
	v_fma_f32 v109, |v107|, s98, 1.0
	v_fma_f32 v154, |v152|, s98, 1.0
	v_fma_f32 v155, |v153|, s98, 1.0
	v_fma_f32 v168, |v166|, s98, 1.0
	v_fma_f32 v169, |v167|, s98, 1.0
	v_fma_f32 v200, |v198|, s98, 1.0
	v_fma_f32 v201, |v199|, s98, 1.0
	v_mul_f32_e32 v110, v108, v109
	v_mul_f32_e32 v156, v154, v155
	v_mul_f32_e32 v170, v168, v169
	v_mul_f32_e32 v202, v200, v201
	v_pk_mul_f32 v[112:113], v[106:107], v[106:107]
	v_pk_mul_f32 v[158:159], v[152:153], v[152:153]
	v_pk_mul_f32 v[172:173], v[166:167], v[166:167]
	v_pk_mul_f32 v[204:205], v[198:199], v[198:199]
	v_rcp_f32_e32 v110, v110
	v_rcp_f32_e32 v156, v156
	v_rcp_f32_e32 v170, v170
	v_rcp_f32_e32 v202, v202
	v_pk_mul_f32 v[112:113], v[112:113], s[100:101] op_sel_hi:[1,0]
	v_pk_mul_f32 v[158:159], v[158:159], s[100:101] op_sel_hi:[1,0]
	v_pk_mul_f32 v[172:173], v[172:173], s[100:101] op_sel_hi:[1,0]
	v_pk_mul_f32 v[204:205], v[204:205], s[100:101] op_sel_hi:[1,0]
	v_pk_mul_f32 v[108:109], v[108:109], v[110:111] op_sel:[1,0] op_sel_hi:[0,0]
	v_pk_mul_f32 v[154:155], v[154:155], v[156:157] op_sel:[1,0] op_sel_hi:[0,0]
	v_pk_mul_f32 v[168:169], v[168:169], v[170:171] op_sel:[1,0] op_sel_hi:[0,0]
	v_pk_mul_f32 v[200:201], v[200:201], v[202:203] op_sel:[1,0] op_sel_hi:[0,0]
	v_exp_f32_e32 v112, v112
	v_exp_f32_e32 v113, v113
	v_exp_f32_e32 v158, v158
	v_exp_f32_e32 v159, v159
	v_exp_f32_e32 v172, v172
	v_exp_f32_e32 v173, v173
	v_exp_f32_e32 v204, v204
	v_exp_f32_e32 v205, v205
	v_pk_fma_f32 v[114:115], v[108:109], s[74:75], v[180:181] op_sel_hi:[1,0,0]
	v_pk_fma_f32 v[160:161], v[154:155], s[74:75], v[180:181] op_sel_hi:[1,0,0]
	v_pk_fma_f32 v[174:175], v[168:169], s[74:75], v[180:181] op_sel_hi:[1,0,0]
	v_pk_fma_f32 v[206:207], v[200:201], s[74:75], v[180:181] op_sel_hi:[1,0,0]
	v_pk_fma_f32 v[114:115], v[108:109], v[114:115], s[78:79] op_sel_hi:[1,1,0]
	v_pk_fma_f32 v[160:161], v[154:155], v[160:161], s[78:79] op_sel_hi:[1,1,0]
	v_pk_fma_f32 v[174:175], v[168:169], v[174:175], s[78:79] op_sel_hi:[1,1,0]
	v_pk_fma_f32 v[206:207], v[200:201], v[206:207], s[78:79] op_sel_hi:[1,1,0]
	v_pk_fma_f32 v[114:115], v[108:109], v[114:115], s[80:81] op_sel_hi:[1,1,0]
	v_pk_fma_f32 v[160:161], v[154:155], v[160:161], s[80:81] op_sel_hi:[1,1,0]
	v_pk_fma_f32 v[174:175], v[168:169], v[174:175], s[80:81] op_sel_hi:[1,1,0]
	v_pk_fma_f32 v[206:207], v[200:201], v[206:207], s[80:81] op_sel_hi:[1,1,0]
	v_pk_fma_f32 v[114:115], v[108:109], v[114:115], s[82:83] op_sel_hi:[1,1,0]
	v_pk_fma_f32 v[160:161], v[154:155], v[160:161], s[82:83] op_sel_hi:[1,1,0]
	v_pk_fma_f32 v[174:175], v[168:169], v[174:175], s[82:83] op_sel_hi:[1,1,0]
	v_pk_fma_f32 v[206:207], v[200:201], v[206:207], s[82:83] op_sel_hi:[1,1,0]
	v_pk_mul_f32 v[114:115], v[108:109], v[114:115]
	v_pk_mul_f32 v[160:161], v[154:155], v[160:161]
	v_pk_mul_f32 v[174:175], v[168:169], v[174:175]
	v_pk_mul_f32 v[206:207], v[200:201], v[206:207]
	v_pk_fma_f32 v[112:113], v[112:113], v[114:115], 1.0 op_sel_hi:[1,1,0] neg_lo:[1,0,0] neg_hi:[1,0,0]
	v_pk_fma_f32 v[158:159], v[158:159], v[160:161], 1.0 op_sel_hi:[1,1,0] neg_lo:[1,0,0] neg_hi:[1,0,0]
	v_pk_fma_f32 v[172:173], v[172:173], v[174:175], 1.0 op_sel_hi:[1,1,0] neg_lo:[1,0,0] neg_hi:[1,0,0]
	v_pk_fma_f32 v[204:205], v[204:205], v[206:207], 1.0 op_sel_hi:[1,1,0] neg_lo:[1,0,0] neg_hi:[1,0,0]
	v_bfi_b32 v113, s34, v113, v107
	v_bfi_b32 v112, s34, v112, v106
	v_bfi_b32 v159, s34, v159, v153
	v_bfi_b32 v158, s34, v158, v152
	v_bfi_b32 v173, s34, v173, v167
	v_bfi_b32 v172, s34, v172, v166
	v_bfi_b32 v205, s34, v205, v199
	v_bfi_b32 v204, s34, v204, v198
	v_pk_mul_f32 v[116:117], v[106:107], 0.5 op_sel_hi:[1,0]
	v_pk_mul_f32 v[162:163], v[152:153], 0.5 op_sel_hi:[1,0]
	v_pk_mul_f32 v[176:177], v[166:167], 0.5 op_sel_hi:[1,0]
	v_pk_mul_f32 v[208:209], v[198:199], 0.5 op_sel_hi:[1,0]
	v_lshlrev_b32_e32 v118, 16, v62
	v_and_b32_e32 v119, 0xffff0000, v62
	v_lshlrev_b32_e32 v164, 16, v63
	v_and_b32_e32 v165, 0xffff0000, v63
	v_lshlrev_b32_e32 v178, 16, v64
	v_and_b32_e32 v179, 0xffff0000, v64
	v_lshlrev_b32_e32 v210, 16, v65
	v_and_b32_e32 v211, 0xffff0000, v65
	v_pk_fma_f32 v[116:117], v[116:117], v[112:113], v[116:117]
	v_pk_fma_f32 v[162:163], v[162:163], v[158:159], v[162:163]
	v_pk_fma_f32 v[176:177], v[176:177], v[172:173], v[176:177]
	v_pk_fma_f32 v[208:209], v[208:209], v[204:205], v[208:209]
	v_pk_mul_f32 v[116:117], v[116:117], v[118:119]
	v_pk_mul_f32 v[162:163], v[162:163], v[164:165]
	v_pk_mul_f32 v[176:177], v[176:177], v[178:179]
	v_pk_mul_f32 v[208:209], v[208:209], v[210:211]
	v_cvt_pk_bf16_f32 v120, v116, v117
	v_cvt_pk_bf16_f32 v121, v162, v163
	v_cvt_pk_bf16_f32 v122, v176, v177
	v_cvt_pk_bf16_f32 v123, v208, v209
	global_store_dwordx4 v[124:125], v[120:123], off nt
	v_lshl_add_u64 v[124:125], v[124:125], 0, s[2:3]
	s_waitcnt lgkmcnt(6)
	v_lshlrev_b32_e32 v82, 16, v24
	v_and_b32_e32 v83, 0xffff0000, v24
	v_lshlrev_b32_e32 v84, 16, v25
	v_and_b32_e32 v85, 0xffff0000, v25
	v_lshlrev_b32_e32 v86, 16, v26
	v_and_b32_e32 v87, 0xffff0000, v26
	v_lshlrev_b32_e32 v88, 16, v27
	v_and_b32_e32 v89, 0xffff0000, v27
	v_pk_fma_f32 v[106:107], v[234:235], v[90:91], v[218:219]
	v_pk_fma_f32 v[152:153], v[236:237], v[92:93], v[220:221]
	v_pk_fma_f32 v[166:167], v[230:231], v[94:95], v[214:215]
	v_pk_fma_f32 v[198:199], v[232:233], v[96:97], v[216:217]
	v_pk_fma_f32 v[106:107], v[238:239], v[98:99], v[106:107]
	v_pk_fma_f32 v[152:153], v[240:241], v[100:101], v[152:153]
	v_pk_fma_f32 v[166:167], v[242:243], v[102:103], v[166:167]
	v_pk_fma_f32 v[198:199], v[244:245], v[104:105], v[198:199]
	v_pk_fma_f32 v[106:107], v[246:247], v[82:83], v[106:107]
	v_pk_fma_f32 v[152:153], v[248:249], v[84:85], v[152:153]
	v_pk_fma_f32 v[166:167], v[250:251], v[86:87], v[166:167]
	v_pk_fma_f32 v[198:199], v[252:253], v[88:89], v[198:199]
	v_fma_f32 v108, |v106|, s98, 1.0
	v_fma_f32 v109, |v107|, s98, 1.0
	v_fma_f32 v154, |v152|, s98, 1.0
	v_fma_f32 v155, |v153|, s98, 1.0
	v_fma_f32 v168, |v166|, s98, 1.0
	v_fma_f32 v169, |v167|, s98, 1.0
	v_fma_f32 v200, |v198|, s98, 1.0
	v_fma_f32 v201, |v199|, s98, 1.0
	v_mul_f32_e32 v110, v108, v109
	v_mul_f32_e32 v156, v154, v155
	v_mul_f32_e32 v170, v168, v169
	v_mul_f32_e32 v202, v200, v201
	v_pk_mul_f32 v[112:113], v[106:107], v[106:107]
	v_pk_mul_f32 v[158:159], v[152:153], v[152:153]
	v_pk_mul_f32 v[172:173], v[166:167], v[166:167]
	v_pk_mul_f32 v[204:205], v[198:199], v[198:199]
	v_rcp_f32_e32 v110, v110
	v_rcp_f32_e32 v156, v156
	v_rcp_f32_e32 v170, v170
	v_rcp_f32_e32 v202, v202
	v_pk_mul_f32 v[112:113], v[112:113], s[100:101] op_sel_hi:[1,0]
	v_pk_mul_f32 v[158:159], v[158:159], s[100:101] op_sel_hi:[1,0]
	v_pk_mul_f32 v[172:173], v[172:173], s[100:101] op_sel_hi:[1,0]
	v_pk_mul_f32 v[204:205], v[204:205], s[100:101] op_sel_hi:[1,0]
	v_pk_mul_f32 v[108:109], v[108:109], v[110:111] op_sel:[1,0] op_sel_hi:[0,0]
	v_pk_mul_f32 v[154:155], v[154:155], v[156:157] op_sel:[1,0] op_sel_hi:[0,0]
	v_pk_mul_f32 v[168:169], v[168:169], v[170:171] op_sel:[1,0] op_sel_hi:[0,0]
	v_pk_mul_f32 v[200:201], v[200:201], v[202:203] op_sel:[1,0] op_sel_hi:[0,0]
	v_exp_f32_e32 v112, v112
	v_exp_f32_e32 v113, v113
	v_exp_f32_e32 v158, v158
	v_exp_f32_e32 v159, v159
	v_exp_f32_e32 v172, v172
	v_exp_f32_e32 v173, v173
	v_exp_f32_e32 v204, v204
	v_exp_f32_e32 v205, v205
	v_pk_fma_f32 v[114:115], v[108:109], s[74:75], v[180:181] op_sel_hi:[1,0,0]
	v_pk_fma_f32 v[160:161], v[154:155], s[74:75], v[180:181] op_sel_hi:[1,0,0]
	v_pk_fma_f32 v[174:175], v[168:169], s[74:75], v[180:181] op_sel_hi:[1,0,0]
	v_pk_fma_f32 v[206:207], v[200:201], s[74:75], v[180:181] op_sel_hi:[1,0,0]
	v_pk_fma_f32 v[114:115], v[108:109], v[114:115], s[78:79] op_sel_hi:[1,1,0]
	v_pk_fma_f32 v[160:161], v[154:155], v[160:161], s[78:79] op_sel_hi:[1,1,0]
	v_pk_fma_f32 v[174:175], v[168:169], v[174:175], s[78:79] op_sel_hi:[1,1,0]
	v_pk_fma_f32 v[206:207], v[200:201], v[206:207], s[78:79] op_sel_hi:[1,1,0]
	v_pk_fma_f32 v[114:115], v[108:109], v[114:115], s[80:81] op_sel_hi:[1,1,0]
	v_pk_fma_f32 v[160:161], v[154:155], v[160:161], s[80:81] op_sel_hi:[1,1,0]
	v_pk_fma_f32 v[174:175], v[168:169], v[174:175], s[80:81] op_sel_hi:[1,1,0]
	v_pk_fma_f32 v[206:207], v[200:201], v[206:207], s[80:81] op_sel_hi:[1,1,0]
	v_pk_fma_f32 v[114:115], v[108:109], v[114:115], s[82:83] op_sel_hi:[1,1,0]
	v_pk_fma_f32 v[160:161], v[154:155], v[160:161], s[82:83] op_sel_hi:[1,1,0]
	v_pk_fma_f32 v[174:175], v[168:169], v[174:175], s[82:83] op_sel_hi:[1,1,0]
	v_pk_fma_f32 v[206:207], v[200:201], v[206:207], s[82:83] op_sel_hi:[1,1,0]
	v_pk_mul_f32 v[114:115], v[108:109], v[114:115]
	v_pk_mul_f32 v[160:161], v[154:155], v[160:161]
	v_pk_mul_f32 v[174:175], v[168:169], v[174:175]
	v_pk_mul_f32 v[206:207], v[200:201], v[206:207]
	v_pk_fma_f32 v[112:113], v[112:113], v[114:115], 1.0 op_sel_hi:[1,1,0] neg_lo:[1,0,0] neg_hi:[1,0,0]
	v_pk_fma_f32 v[158:159], v[158:159], v[160:161], 1.0 op_sel_hi:[1,1,0] neg_lo:[1,0,0] neg_hi:[1,0,0]
	v_pk_fma_f32 v[172:173], v[172:173], v[174:175], 1.0 op_sel_hi:[1,1,0] neg_lo:[1,0,0] neg_hi:[1,0,0]
	v_pk_fma_f32 v[204:205], v[204:205], v[206:207], 1.0 op_sel_hi:[1,1,0] neg_lo:[1,0,0] neg_hi:[1,0,0]
	v_bfi_b32 v113, s34, v113, v107
	v_bfi_b32 v112, s34, v112, v106
	v_bfi_b32 v159, s34, v159, v153
	v_bfi_b32 v158, s34, v158, v152
	v_bfi_b32 v173, s34, v173, v167
	v_bfi_b32 v172, s34, v172, v166
	v_bfi_b32 v205, s34, v205, v199
	v_bfi_b32 v204, s34, v204, v198
	v_pk_mul_f32 v[116:117], v[106:107], 0.5 op_sel_hi:[1,0]
	v_pk_mul_f32 v[162:163], v[152:153], 0.5 op_sel_hi:[1,0]
	v_pk_mul_f32 v[176:177], v[166:167], 0.5 op_sel_hi:[1,0]
	v_pk_mul_f32 v[208:209], v[198:199], 0.5 op_sel_hi:[1,0]
	v_lshlrev_b32_e32 v118, 16, v66
	v_and_b32_e32 v119, 0xffff0000, v66
	v_lshlrev_b32_e32 v164, 16, v67
	v_and_b32_e32 v165, 0xffff0000, v67
	v_lshlrev_b32_e32 v178, 16, v68
	v_and_b32_e32 v179, 0xffff0000, v68
	v_lshlrev_b32_e32 v210, 16, v69
	v_and_b32_e32 v211, 0xffff0000, v69
	v_pk_fma_f32 v[116:117], v[116:117], v[112:113], v[116:117]
	v_pk_fma_f32 v[162:163], v[162:163], v[158:159], v[162:163]
	v_pk_fma_f32 v[176:177], v[176:177], v[172:173], v[176:177]
	v_pk_fma_f32 v[208:209], v[208:209], v[204:205], v[208:209]
	v_pk_mul_f32 v[116:117], v[116:117], v[118:119]
	v_pk_mul_f32 v[162:163], v[162:163], v[164:165]
	v_pk_mul_f32 v[176:177], v[176:177], v[178:179]
	v_pk_mul_f32 v[208:209], v[208:209], v[210:211]
	v_cvt_pk_bf16_f32 v120, v116, v117
	v_cvt_pk_bf16_f32 v121, v162, v163
	v_cvt_pk_bf16_f32 v122, v176, v177
	v_cvt_pk_bf16_f32 v123, v208, v209
	global_store_dwordx4 v[124:125], v[120:123], off nt
	v_lshl_add_u64 v[124:125], v[124:125], 0, s[2:3]
	s_waitcnt lgkmcnt(4)
	v_lshlrev_b32_e32 v90, 16, v28
	v_and_b32_e32 v91, 0xffff0000, v28
	v_lshlrev_b32_e32 v92, 16, v29
	v_and_b32_e32 v93, 0xffff0000, v29
	v_lshlrev_b32_e32 v94, 16, v30
	v_and_b32_e32 v95, 0xffff0000, v30
	v_lshlrev_b32_e32 v96, 16, v31
	v_and_b32_e32 v97, 0xffff0000, v31
	v_pk_fma_f32 v[106:107], v[234:235], v[98:99], v[218:219]
	v_pk_fma_f32 v[152:153], v[236:237], v[100:101], v[220:221]
	v_pk_fma_f32 v[166:167], v[230:231], v[102:103], v[214:215]
	v_pk_fma_f32 v[198:199], v[232:233], v[104:105], v[216:217]
	v_pk_fma_f32 v[106:107], v[238:239], v[82:83], v[106:107]
	v_pk_fma_f32 v[152:153], v[240:241], v[84:85], v[152:153]
	v_pk_fma_f32 v[166:167], v[242:243], v[86:87], v[166:167]
	v_pk_fma_f32 v[198:199], v[244:245], v[88:89], v[198:199]
	v_pk_fma_f32 v[106:107], v[246:247], v[90:91], v[106:107]
	v_pk_fma_f32 v[152:153], v[248:249], v[92:93], v[152:153]
	v_pk_fma_f32 v[166:167], v[250:251], v[94:95], v[166:167]
	v_pk_fma_f32 v[198:199], v[252:253], v[96:97], v[198:199]
	v_fma_f32 v108, |v106|, s98, 1.0
	v_fma_f32 v109, |v107|, s98, 1.0
	v_fma_f32 v154, |v152|, s98, 1.0
	v_fma_f32 v155, |v153|, s98, 1.0
	v_fma_f32 v168, |v166|, s98, 1.0
	v_fma_f32 v169, |v167|, s98, 1.0
	v_fma_f32 v200, |v198|, s98, 1.0
	v_fma_f32 v201, |v199|, s98, 1.0
	v_mul_f32_e32 v110, v108, v109
	v_mul_f32_e32 v156, v154, v155
	v_mul_f32_e32 v170, v168, v169
	v_mul_f32_e32 v202, v200, v201
	v_pk_mul_f32 v[112:113], v[106:107], v[106:107]
	v_pk_mul_f32 v[158:159], v[152:153], v[152:153]
	v_pk_mul_f32 v[172:173], v[166:167], v[166:167]
	v_pk_mul_f32 v[204:205], v[198:199], v[198:199]
	v_rcp_f32_e32 v110, v110
	v_rcp_f32_e32 v156, v156
	v_rcp_f32_e32 v170, v170
	v_rcp_f32_e32 v202, v202
	v_pk_mul_f32 v[112:113], v[112:113], s[100:101] op_sel_hi:[1,0]
	v_pk_mul_f32 v[158:159], v[158:159], s[100:101] op_sel_hi:[1,0]
	v_pk_mul_f32 v[172:173], v[172:173], s[100:101] op_sel_hi:[1,0]
	v_pk_mul_f32 v[204:205], v[204:205], s[100:101] op_sel_hi:[1,0]
	v_pk_mul_f32 v[108:109], v[108:109], v[110:111] op_sel:[1,0] op_sel_hi:[0,0]
	v_pk_mul_f32 v[154:155], v[154:155], v[156:157] op_sel:[1,0] op_sel_hi:[0,0]
	v_pk_mul_f32 v[168:169], v[168:169], v[170:171] op_sel:[1,0] op_sel_hi:[0,0]
	v_pk_mul_f32 v[200:201], v[200:201], v[202:203] op_sel:[1,0] op_sel_hi:[0,0]
	v_exp_f32_e32 v112, v112
	v_exp_f32_e32 v113, v113
	v_exp_f32_e32 v158, v158
	v_exp_f32_e32 v159, v159
	v_exp_f32_e32 v172, v172
	v_exp_f32_e32 v173, v173
	v_exp_f32_e32 v204, v204
	v_exp_f32_e32 v205, v205
	v_pk_fma_f32 v[114:115], v[108:109], s[74:75], v[180:181] op_sel_hi:[1,0,0]
	v_pk_fma_f32 v[160:161], v[154:155], s[74:75], v[180:181] op_sel_hi:[1,0,0]
	v_pk_fma_f32 v[174:175], v[168:169], s[74:75], v[180:181] op_sel_hi:[1,0,0]
	v_pk_fma_f32 v[206:207], v[200:201], s[74:75], v[180:181] op_sel_hi:[1,0,0]
	v_pk_fma_f32 v[114:115], v[108:109], v[114:115], s[78:79] op_sel_hi:[1,1,0]
	v_pk_fma_f32 v[160:161], v[154:155], v[160:161], s[78:79] op_sel_hi:[1,1,0]
	v_pk_fma_f32 v[174:175], v[168:169], v[174:175], s[78:79] op_sel_hi:[1,1,0]
	v_pk_fma_f32 v[206:207], v[200:201], v[206:207], s[78:79] op_sel_hi:[1,1,0]
	v_pk_fma_f32 v[114:115], v[108:109], v[114:115], s[80:81] op_sel_hi:[1,1,0]
	v_pk_fma_f32 v[160:161], v[154:155], v[160:161], s[80:81] op_sel_hi:[1,1,0]
	v_pk_fma_f32 v[174:175], v[168:169], v[174:175], s[80:81] op_sel_hi:[1,1,0]
	v_pk_fma_f32 v[206:207], v[200:201], v[206:207], s[80:81] op_sel_hi:[1,1,0]
	v_pk_fma_f32 v[114:115], v[108:109], v[114:115], s[82:83] op_sel_hi:[1,1,0]
	v_pk_fma_f32 v[160:161], v[154:155], v[160:161], s[82:83] op_sel_hi:[1,1,0]
	v_pk_fma_f32 v[174:175], v[168:169], v[174:175], s[82:83] op_sel_hi:[1,1,0]
	v_pk_fma_f32 v[206:207], v[200:201], v[206:207], s[82:83] op_sel_hi:[1,1,0]
	v_pk_mul_f32 v[114:115], v[108:109], v[114:115]
	v_pk_mul_f32 v[160:161], v[154:155], v[160:161]
	v_pk_mul_f32 v[174:175], v[168:169], v[174:175]
	v_pk_mul_f32 v[206:207], v[200:201], v[206:207]
	v_pk_fma_f32 v[112:113], v[112:113], v[114:115], 1.0 op_sel_hi:[1,1,0] neg_lo:[1,0,0] neg_hi:[1,0,0]
	v_pk_fma_f32 v[158:159], v[158:159], v[160:161], 1.0 op_sel_hi:[1,1,0] neg_lo:[1,0,0] neg_hi:[1,0,0]
	v_pk_fma_f32 v[172:173], v[172:173], v[174:175], 1.0 op_sel_hi:[1,1,0] neg_lo:[1,0,0] neg_hi:[1,0,0]
	v_pk_fma_f32 v[204:205], v[204:205], v[206:207], 1.0 op_sel_hi:[1,1,0] neg_lo:[1,0,0] neg_hi:[1,0,0]
	v_bfi_b32 v113, s34, v113, v107
	v_bfi_b32 v112, s34, v112, v106
	v_bfi_b32 v159, s34, v159, v153
	v_bfi_b32 v158, s34, v158, v152
	v_bfi_b32 v173, s34, v173, v167
	v_bfi_b32 v172, s34, v172, v166
	v_bfi_b32 v205, s34, v205, v199
	v_bfi_b32 v204, s34, v204, v198
	v_pk_mul_f32 v[116:117], v[106:107], 0.5 op_sel_hi:[1,0]
	v_pk_mul_f32 v[162:163], v[152:153], 0.5 op_sel_hi:[1,0]
	v_pk_mul_f32 v[176:177], v[166:167], 0.5 op_sel_hi:[1,0]
	v_pk_mul_f32 v[208:209], v[198:199], 0.5 op_sel_hi:[1,0]
	v_lshlrev_b32_e32 v118, 16, v70
	v_and_b32_e32 v119, 0xffff0000, v70
	v_lshlrev_b32_e32 v164, 16, v71
	v_and_b32_e32 v165, 0xffff0000, v71
	v_lshlrev_b32_e32 v178, 16, v72
	v_and_b32_e32 v179, 0xffff0000, v72
	v_lshlrev_b32_e32 v210, 16, v73
	v_and_b32_e32 v211, 0xffff0000, v73
	v_pk_fma_f32 v[116:117], v[116:117], v[112:113], v[116:117]
	v_pk_fma_f32 v[162:163], v[162:163], v[158:159], v[162:163]
	v_pk_fma_f32 v[176:177], v[176:177], v[172:173], v[176:177]
	v_pk_fma_f32 v[208:209], v[208:209], v[204:205], v[208:209]
	v_pk_mul_f32 v[116:117], v[116:117], v[118:119]
	v_pk_mul_f32 v[162:163], v[162:163], v[164:165]
	v_pk_mul_f32 v[176:177], v[176:177], v[178:179]
	v_pk_mul_f32 v[208:209], v[208:209], v[210:211]
	v_cvt_pk_bf16_f32 v120, v116, v117
	v_cvt_pk_bf16_f32 v121, v162, v163
	v_cvt_pk_bf16_f32 v122, v176, v177
	v_cvt_pk_bf16_f32 v123, v208, v209
	global_store_dwordx4 v[124:125], v[120:123], off nt
	v_lshl_add_u64 v[124:125], v[124:125], 0, s[2:3]
	s_waitcnt lgkmcnt(2)
	v_lshlrev_b32_e32 v98, 16, v32
	v_and_b32_e32 v99, 0xffff0000, v32
	v_lshlrev_b32_e32 v100, 16, v33
	v_and_b32_e32 v101, 0xffff0000, v33
	v_lshlrev_b32_e32 v102, 16, v34
	v_and_b32_e32 v103, 0xffff0000, v34
	v_lshlrev_b32_e32 v104, 16, v35
	v_and_b32_e32 v105, 0xffff0000, v35
	v_pk_fma_f32 v[106:107], v[234:235], v[82:83], v[218:219]
	v_pk_fma_f32 v[152:153], v[236:237], v[84:85], v[220:221]
	v_pk_fma_f32 v[166:167], v[230:231], v[86:87], v[214:215]
	v_pk_fma_f32 v[198:199], v[232:233], v[88:89], v[216:217]
	v_pk_fma_f32 v[106:107], v[238:239], v[90:91], v[106:107]
	v_pk_fma_f32 v[152:153], v[240:241], v[92:93], v[152:153]
	v_pk_fma_f32 v[166:167], v[242:243], v[94:95], v[166:167]
	v_pk_fma_f32 v[198:199], v[244:245], v[96:97], v[198:199]
	v_pk_fma_f32 v[106:107], v[246:247], v[98:99], v[106:107]
	v_pk_fma_f32 v[152:153], v[248:249], v[100:101], v[152:153]
	v_pk_fma_f32 v[166:167], v[250:251], v[102:103], v[166:167]
	v_pk_fma_f32 v[198:199], v[252:253], v[104:105], v[198:199]
	v_fma_f32 v108, |v106|, s98, 1.0
	v_fma_f32 v109, |v107|, s98, 1.0
	v_fma_f32 v154, |v152|, s98, 1.0
	v_fma_f32 v155, |v153|, s98, 1.0
	v_fma_f32 v168, |v166|, s98, 1.0
	v_fma_f32 v169, |v167|, s98, 1.0
	v_fma_f32 v200, |v198|, s98, 1.0
	v_fma_f32 v201, |v199|, s98, 1.0
	v_mul_f32_e32 v110, v108, v109
	v_mul_f32_e32 v156, v154, v155
	v_mul_f32_e32 v170, v168, v169
	v_mul_f32_e32 v202, v200, v201
	v_pk_mul_f32 v[112:113], v[106:107], v[106:107]
	v_pk_mul_f32 v[158:159], v[152:153], v[152:153]
	v_pk_mul_f32 v[172:173], v[166:167], v[166:167]
	v_pk_mul_f32 v[204:205], v[198:199], v[198:199]
	v_rcp_f32_e32 v110, v110
	v_rcp_f32_e32 v156, v156
	v_rcp_f32_e32 v170, v170
	v_rcp_f32_e32 v202, v202
	v_pk_mul_f32 v[112:113], v[112:113], s[100:101] op_sel_hi:[1,0]
	v_pk_mul_f32 v[158:159], v[158:159], s[100:101] op_sel_hi:[1,0]
	v_pk_mul_f32 v[172:173], v[172:173], s[100:101] op_sel_hi:[1,0]
	v_pk_mul_f32 v[204:205], v[204:205], s[100:101] op_sel_hi:[1,0]
	v_pk_mul_f32 v[108:109], v[108:109], v[110:111] op_sel:[1,0] op_sel_hi:[0,0]
	v_pk_mul_f32 v[154:155], v[154:155], v[156:157] op_sel:[1,0] op_sel_hi:[0,0]
	v_pk_mul_f32 v[168:169], v[168:169], v[170:171] op_sel:[1,0] op_sel_hi:[0,0]
	v_pk_mul_f32 v[200:201], v[200:201], v[202:203] op_sel:[1,0] op_sel_hi:[0,0]
	v_exp_f32_e32 v112, v112
	v_exp_f32_e32 v113, v113
	v_exp_f32_e32 v158, v158
	v_exp_f32_e32 v159, v159
	v_exp_f32_e32 v172, v172
	v_exp_f32_e32 v173, v173
	v_exp_f32_e32 v204, v204
	v_exp_f32_e32 v205, v205
	v_pk_fma_f32 v[114:115], v[108:109], s[74:75], v[180:181] op_sel_hi:[1,0,0]
	v_pk_fma_f32 v[160:161], v[154:155], s[74:75], v[180:181] op_sel_hi:[1,0,0]
	v_pk_fma_f32 v[174:175], v[168:169], s[74:75], v[180:181] op_sel_hi:[1,0,0]
	v_pk_fma_f32 v[206:207], v[200:201], s[74:75], v[180:181] op_sel_hi:[1,0,0]
	v_pk_fma_f32 v[114:115], v[108:109], v[114:115], s[78:79] op_sel_hi:[1,1,0]
	v_pk_fma_f32 v[160:161], v[154:155], v[160:161], s[78:79] op_sel_hi:[1,1,0]
	v_pk_fma_f32 v[174:175], v[168:169], v[174:175], s[78:79] op_sel_hi:[1,1,0]
	v_pk_fma_f32 v[206:207], v[200:201], v[206:207], s[78:79] op_sel_hi:[1,1,0]
	v_pk_fma_f32 v[114:115], v[108:109], v[114:115], s[80:81] op_sel_hi:[1,1,0]
	v_pk_fma_f32 v[160:161], v[154:155], v[160:161], s[80:81] op_sel_hi:[1,1,0]
	v_pk_fma_f32 v[174:175], v[168:169], v[174:175], s[80:81] op_sel_hi:[1,1,0]
	v_pk_fma_f32 v[206:207], v[200:201], v[206:207], s[80:81] op_sel_hi:[1,1,0]
	v_pk_fma_f32 v[114:115], v[108:109], v[114:115], s[82:83] op_sel_hi:[1,1,0]
	v_pk_fma_f32 v[160:161], v[154:155], v[160:161], s[82:83] op_sel_hi:[1,1,0]
	v_pk_fma_f32 v[174:175], v[168:169], v[174:175], s[82:83] op_sel_hi:[1,1,0]
	v_pk_fma_f32 v[206:207], v[200:201], v[206:207], s[82:83] op_sel_hi:[1,1,0]
	v_pk_mul_f32 v[114:115], v[108:109], v[114:115]
	v_pk_mul_f32 v[160:161], v[154:155], v[160:161]
	v_pk_mul_f32 v[174:175], v[168:169], v[174:175]
	v_pk_mul_f32 v[206:207], v[200:201], v[206:207]
	v_pk_fma_f32 v[112:113], v[112:113], v[114:115], 1.0 op_sel_hi:[1,1,0] neg_lo:[1,0,0] neg_hi:[1,0,0]
	v_pk_fma_f32 v[158:159], v[158:159], v[160:161], 1.0 op_sel_hi:[1,1,0] neg_lo:[1,0,0] neg_hi:[1,0,0]
	v_pk_fma_f32 v[172:173], v[172:173], v[174:175], 1.0 op_sel_hi:[1,1,0] neg_lo:[1,0,0] neg_hi:[1,0,0]
	v_pk_fma_f32 v[204:205], v[204:205], v[206:207], 1.0 op_sel_hi:[1,1,0] neg_lo:[1,0,0] neg_hi:[1,0,0]
	v_bfi_b32 v113, s34, v113, v107
	v_bfi_b32 v112, s34, v112, v106
	v_bfi_b32 v159, s34, v159, v153
	v_bfi_b32 v158, s34, v158, v152
	v_bfi_b32 v173, s34, v173, v167
	v_bfi_b32 v172, s34, v172, v166
	v_bfi_b32 v205, s34, v205, v199
	v_bfi_b32 v204, s34, v204, v198
	v_pk_mul_f32 v[116:117], v[106:107], 0.5 op_sel_hi:[1,0]
	v_pk_mul_f32 v[162:163], v[152:153], 0.5 op_sel_hi:[1,0]
	v_pk_mul_f32 v[176:177], v[166:167], 0.5 op_sel_hi:[1,0]
	v_pk_mul_f32 v[208:209], v[198:199], 0.5 op_sel_hi:[1,0]
	v_lshlrev_b32_e32 v118, 16, v74
	v_and_b32_e32 v119, 0xffff0000, v74
	v_lshlrev_b32_e32 v164, 16, v75
	v_and_b32_e32 v165, 0xffff0000, v75
	v_lshlrev_b32_e32 v178, 16, v76
	v_and_b32_e32 v179, 0xffff0000, v76
	v_lshlrev_b32_e32 v210, 16, v77
	v_and_b32_e32 v211, 0xffff0000, v77
	v_pk_fma_f32 v[116:117], v[116:117], v[112:113], v[116:117]
	v_pk_fma_f32 v[162:163], v[162:163], v[158:159], v[162:163]
	v_pk_fma_f32 v[176:177], v[176:177], v[172:173], v[176:177]
	v_pk_fma_f32 v[208:209], v[208:209], v[204:205], v[208:209]
	v_pk_mul_f32 v[116:117], v[116:117], v[118:119]
	v_pk_mul_f32 v[162:163], v[162:163], v[164:165]
	v_pk_mul_f32 v[176:177], v[176:177], v[178:179]
	v_pk_mul_f32 v[208:209], v[208:209], v[210:211]
	v_cvt_pk_bf16_f32 v120, v116, v117
	v_cvt_pk_bf16_f32 v121, v162, v163
	v_cvt_pk_bf16_f32 v122, v176, v177
	v_cvt_pk_bf16_f32 v123, v208, v209
	global_store_dwordx4 v[124:125], v[120:123], off nt
	v_lshl_add_u64 v[124:125], v[124:125], 0, s[2:3]
	s_waitcnt lgkmcnt(0)
	v_lshlrev_b32_e32 v82, 16, v36
	v_and_b32_e32 v83, 0xffff0000, v36
	v_lshlrev_b32_e32 v84, 16, v37
	v_and_b32_e32 v85, 0xffff0000, v37
	v_lshlrev_b32_e32 v86, 16, v38
	v_and_b32_e32 v87, 0xffff0000, v38
	v_lshlrev_b32_e32 v88, 16, v39
	v_and_b32_e32 v89, 0xffff0000, v39
	v_pk_fma_f32 v[106:107], v[234:235], v[90:91], v[218:219]
	v_pk_fma_f32 v[152:153], v[236:237], v[92:93], v[220:221]
	v_pk_fma_f32 v[166:167], v[230:231], v[94:95], v[214:215]
	v_pk_fma_f32 v[198:199], v[232:233], v[96:97], v[216:217]
	v_pk_fma_f32 v[106:107], v[238:239], v[98:99], v[106:107]
	v_pk_fma_f32 v[152:153], v[240:241], v[100:101], v[152:153]
	v_pk_fma_f32 v[166:167], v[242:243], v[102:103], v[166:167]
	v_pk_fma_f32 v[198:199], v[244:245], v[104:105], v[198:199]
	v_pk_fma_f32 v[106:107], v[246:247], v[82:83], v[106:107]
	v_pk_fma_f32 v[152:153], v[248:249], v[84:85], v[152:153]
	v_pk_fma_f32 v[166:167], v[250:251], v[86:87], v[166:167]
	v_pk_fma_f32 v[198:199], v[252:253], v[88:89], v[198:199]
	v_fma_f32 v108, |v106|, s98, 1.0
	v_fma_f32 v109, |v107|, s98, 1.0
	v_fma_f32 v154, |v152|, s98, 1.0
	v_fma_f32 v155, |v153|, s98, 1.0
	v_fma_f32 v168, |v166|, s98, 1.0
	v_fma_f32 v169, |v167|, s98, 1.0
	v_fma_f32 v200, |v198|, s98, 1.0
	v_fma_f32 v201, |v199|, s98, 1.0
	v_mul_f32_e32 v110, v108, v109
	v_mul_f32_e32 v156, v154, v155
	v_mul_f32_e32 v170, v168, v169
	v_mul_f32_e32 v202, v200, v201
	v_pk_mul_f32 v[112:113], v[106:107], v[106:107]
	v_pk_mul_f32 v[158:159], v[152:153], v[152:153]
	v_pk_mul_f32 v[172:173], v[166:167], v[166:167]
	v_pk_mul_f32 v[204:205], v[198:199], v[198:199]
	v_rcp_f32_e32 v110, v110
	v_rcp_f32_e32 v156, v156
	v_rcp_f32_e32 v170, v170
	v_rcp_f32_e32 v202, v202
	v_pk_mul_f32 v[112:113], v[112:113], s[100:101] op_sel_hi:[1,0]
	v_pk_mul_f32 v[158:159], v[158:159], s[100:101] op_sel_hi:[1,0]
	v_pk_mul_f32 v[172:173], v[172:173], s[100:101] op_sel_hi:[1,0]
	v_pk_mul_f32 v[204:205], v[204:205], s[100:101] op_sel_hi:[1,0]
	v_pk_mul_f32 v[108:109], v[108:109], v[110:111] op_sel:[1,0] op_sel_hi:[0,0]
	v_pk_mul_f32 v[154:155], v[154:155], v[156:157] op_sel:[1,0] op_sel_hi:[0,0]
	v_pk_mul_f32 v[168:169], v[168:169], v[170:171] op_sel:[1,0] op_sel_hi:[0,0]
	v_pk_mul_f32 v[200:201], v[200:201], v[202:203] op_sel:[1,0] op_sel_hi:[0,0]
	v_exp_f32_e32 v112, v112
	v_exp_f32_e32 v113, v113
	v_exp_f32_e32 v158, v158
	v_exp_f32_e32 v159, v159
	v_exp_f32_e32 v172, v172
	v_exp_f32_e32 v173, v173
	v_exp_f32_e32 v204, v204
	v_exp_f32_e32 v205, v205
	v_pk_fma_f32 v[114:115], v[108:109], s[74:75], v[180:181] op_sel_hi:[1,0,0]
	v_pk_fma_f32 v[160:161], v[154:155], s[74:75], v[180:181] op_sel_hi:[1,0,0]
	v_pk_fma_f32 v[174:175], v[168:169], s[74:75], v[180:181] op_sel_hi:[1,0,0]
	v_pk_fma_f32 v[206:207], v[200:201], s[74:75], v[180:181] op_sel_hi:[1,0,0]
	v_pk_fma_f32 v[114:115], v[108:109], v[114:115], s[78:79] op_sel_hi:[1,1,0]
	v_pk_fma_f32 v[160:161], v[154:155], v[160:161], s[78:79] op_sel_hi:[1,1,0]
	v_pk_fma_f32 v[174:175], v[168:169], v[174:175], s[78:79] op_sel_hi:[1,1,0]
	v_pk_fma_f32 v[206:207], v[200:201], v[206:207], s[78:79] op_sel_hi:[1,1,0]
	v_pk_fma_f32 v[114:115], v[108:109], v[114:115], s[80:81] op_sel_hi:[1,1,0]
	v_pk_fma_f32 v[160:161], v[154:155], v[160:161], s[80:81] op_sel_hi:[1,1,0]
	v_pk_fma_f32 v[174:175], v[168:169], v[174:175], s[80:81] op_sel_hi:[1,1,0]
	v_pk_fma_f32 v[206:207], v[200:201], v[206:207], s[80:81] op_sel_hi:[1,1,0]
	v_pk_fma_f32 v[114:115], v[108:109], v[114:115], s[82:83] op_sel_hi:[1,1,0]
	v_pk_fma_f32 v[160:161], v[154:155], v[160:161], s[82:83] op_sel_hi:[1,1,0]
	v_pk_fma_f32 v[174:175], v[168:169], v[174:175], s[82:83] op_sel_hi:[1,1,0]
	v_pk_fma_f32 v[206:207], v[200:201], v[206:207], s[82:83] op_sel_hi:[1,1,0]
	v_pk_mul_f32 v[114:115], v[108:109], v[114:115]
	v_pk_mul_f32 v[160:161], v[154:155], v[160:161]
	v_pk_mul_f32 v[174:175], v[168:169], v[174:175]
	v_pk_mul_f32 v[206:207], v[200:201], v[206:207]
	v_pk_fma_f32 v[112:113], v[112:113], v[114:115], 1.0 op_sel_hi:[1,1,0] neg_lo:[1,0,0] neg_hi:[1,0,0]
	v_pk_fma_f32 v[158:159], v[158:159], v[160:161], 1.0 op_sel_hi:[1,1,0] neg_lo:[1,0,0] neg_hi:[1,0,0]
	v_pk_fma_f32 v[172:173], v[172:173], v[174:175], 1.0 op_sel_hi:[1,1,0] neg_lo:[1,0,0] neg_hi:[1,0,0]
	v_pk_fma_f32 v[204:205], v[204:205], v[206:207], 1.0 op_sel_hi:[1,1,0] neg_lo:[1,0,0] neg_hi:[1,0,0]
	v_bfi_b32 v113, s34, v113, v107
	v_bfi_b32 v112, s34, v112, v106
	v_bfi_b32 v159, s34, v159, v153
	v_bfi_b32 v158, s34, v158, v152
	v_bfi_b32 v173, s34, v173, v167
	v_bfi_b32 v172, s34, v172, v166
	v_bfi_b32 v205, s34, v205, v199
	v_bfi_b32 v204, s34, v204, v198
	v_pk_mul_f32 v[116:117], v[106:107], 0.5 op_sel_hi:[1,0]
	v_pk_mul_f32 v[162:163], v[152:153], 0.5 op_sel_hi:[1,0]
	v_pk_mul_f32 v[176:177], v[166:167], 0.5 op_sel_hi:[1,0]
	v_pk_mul_f32 v[208:209], v[198:199], 0.5 op_sel_hi:[1,0]
	v_lshlrev_b32_e32 v118, 16, v78
	v_and_b32_e32 v119, 0xffff0000, v78
	v_lshlrev_b32_e32 v164, 16, v79
	v_and_b32_e32 v165, 0xffff0000, v79
	v_lshlrev_b32_e32 v178, 16, v80
	v_and_b32_e32 v179, 0xffff0000, v80
	v_lshlrev_b32_e32 v210, 16, v81
	v_and_b32_e32 v211, 0xffff0000, v81
	v_pk_fma_f32 v[116:117], v[116:117], v[112:113], v[116:117]
	v_pk_fma_f32 v[162:163], v[162:163], v[158:159], v[162:163]
	v_pk_fma_f32 v[176:177], v[176:177], v[172:173], v[176:177]
	v_pk_fma_f32 v[208:209], v[208:209], v[204:205], v[208:209]
	v_pk_mul_f32 v[116:117], v[116:117], v[118:119]
	v_pk_mul_f32 v[162:163], v[162:163], v[164:165]
	v_pk_mul_f32 v[176:177], v[176:177], v[178:179]
	v_pk_mul_f32 v[208:209], v[208:209], v[210:211]
	v_cvt_pk_bf16_f32 v120, v116, v117
	v_cvt_pk_bf16_f32 v121, v162, v163
	v_cvt_pk_bf16_f32 v122, v176, v177
	v_cvt_pk_bf16_f32 v123, v208, v209
	v_cmp_ne_u32_e32 vcc, 31, v183
	s_and_saveexec_b64 s[94:95], vcc
	global_store_dwordx4 v[124:125], v[120:123], off nt
	s_mov_b64 exec, s[94:95]
	s_branch .LBB0_2297

.LBB0_2308:
	v_add_u32_e32 v46, s36, v45
	v_subrev_u32_e32 v48, 32, v46
	v_subrev_u32_e32 v32, 32, v45
	v_cmp_gt_u32_e32 vcc, s50, v32
	v_cmp_gt_i32_e64 s[2:3], s81, v48
	s_and_b64 s[94:95], vcc, s[2:3]
	v_add_u32_e32 v47, s44, v44
	s_and_saveexec_b64 s[2:3], s[94:95]
	s_cbranch_execz .LBB0_2310
	v_add_u32_e32 v32, 0xfffffef0, v47
	ds_read_b128 v[50:53], v32
	ds_read_b128 v[36:39], v47
	ds_read_b128 v[54:57], v47 offset:272
	v_and_b32_e32 v42, 0xfff, v48
	v_cmp_eq_u32_e32 vcc, 0, v42
	v_add_u32_e32 v32, 0x11000, v47
	ds_read_b128 v[32:35], v32
	s_waitcnt lgkmcnt(3)
	v_cndmask_b32_e64 v43, v50, 0, vcc
	v_cndmask_b32_e64 v49, v51, 0, vcc
	v_cndmask_b32_e64 v60, v53, 0, vcc
	v_cndmask_b32_e64 v61, v52, 0, vcc
	v_cmp_eq_u32_e32 vcc, s79, v42
	v_lshlrev_b32_e32 v42, 16, v43
	v_and_b32_e32 v43, 0xffff0000, v43
	s_waitcnt lgkmcnt(1)
	v_cndmask_b32_e64 v52, v54, 0, vcc
	v_pk_mul_f32 v[42:43], v[234:235], v[42:43]
	v_lshlrev_b32_e32 v50, 16, v36
	v_and_b32_e32 v51, 0xffff0000, v36
	v_pk_fma_f32 v[42:43], v[238:239], v[50:51], v[42:43]
	v_lshlrev_b32_e32 v50, 16, v52
	v_and_b32_e32 v51, 0xffff0000, v52
	v_pk_fma_f32 v[42:43], v[246:247], v[50:51], v[42:43]
	v_cndmask_b32_e64 v62, v55, 0, vcc
	v_pk_add_f32 v[50:51], v[218:219], v[42:43]
	v_cndmask_b32_e64 v63, v57, 0, vcc
	v_pk_mul_f32 v[52:53], v[50:51], s[70:71] op_sel_hi:[1,0]
	v_cndmask_b32_e64 v64, v56, 0, vcc
	v_and_b32_e32 v54, 0x7fffffff, v52
	v_and_b32_e32 v55, 0x7fffffff, v53
	v_pk_fma_f32 v[42:43], v[54:55], s[72:73], 1.0 op_sel_hi:[1,0,0]
	v_pk_mul_f32 v[54:55], v[54:55], v[54:55]
	v_rcp_f32_e32 v56, v42
	v_rcp_f32_e32 v57, v43
	v_mov_b64_e32 v[42:43], s[76:77]
	v_pk_mul_f32 v[54:55], v[54:55], s[84:85] op_sel_hi:[1,0]
	v_pk_mul_f32 v[50:51], v[50:51], 0.5 op_sel_hi:[1,0]
	v_pk_fma_f32 v[58:59], v[56:57], s[74:75], v[42:43] op_sel_hi:[1,0,0]
	v_exp_f32_e32 v54, v54
	v_pk_fma_f32 v[58:59], v[56:57], v[58:59], s[78:79] op_sel_hi:[1,1,0]
	v_exp_f32_e32 v55, v55
	v_pk_fma_f32 v[58:59], v[56:57], v[58:59], s[80:81] op_sel_hi:[1,1,0]
	v_lshlrev_b32_e32 v36, 16, v37
	v_pk_fma_f32 v[58:59], v[56:57], v[58:59], s[82:83] op_sel_hi:[1,1,0]
	v_and_b32_e32 v37, 0xffff0000, v37
	v_pk_mul_f32 v[56:57], v[56:57], v[58:59]
	s_nop 0
	v_pk_fma_f32 v[54:55], v[54:55], v[56:57], 1.0 op_sel_hi:[1,1,0] neg_lo:[1,0,0] neg_hi:[1,0,0]
	s_nop 0
	v_bfi_b32 v53, s34, v55, v53
	v_bfi_b32 v52, s34, v54, v52
	v_pk_add_f32 v[52:53], v[52:53], 1.0 op_sel_hi:[1,0]
	s_nop 0
	v_pk_mul_f32 v[50:51], v[50:51], v[52:53]
	s_waitcnt lgkmcnt(0)
	v_lshlrev_b32_e32 v52, 16, v32
	v_and_b32_e32 v53, 0xffff0000, v32
	v_pk_mul_f32 v[50:51], v[50:51], v[52:53]
	s_nop 0
	v_cvt_pk_bf16_f32 v32, v50, v51
	v_lshlrev_b32_e32 v50, 16, v49
	v_and_b32_e32 v51, 0xffff0000, v49
	v_pk_mul_f32 v[50:51], v[236:237], v[50:51]
	s_nop 0
	v_pk_fma_f32 v[36:37], v[240:241], v[36:37], v[50:51]
	v_lshlrev_b32_e32 v50, 16, v62
	v_and_b32_e32 v51, 0xffff0000, v62
	v_pk_fma_f32 v[36:37], v[248:249], v[50:51], v[36:37]
	s_nop 0
	v_pk_add_f32 v[36:37], v[220:221], v[36:37]
	s_nop 0
	v_pk_mul_f32 v[50:51], v[36:37], s[70:71] op_sel_hi:[1,0]
	v_pk_mul_f32 v[36:37], v[36:37], 0.5 op_sel_hi:[1,0]
	v_and_b32_e32 v52, 0x7fffffff, v50
	v_and_b32_e32 v53, 0x7fffffff, v51
	v_pk_fma_f32 v[54:55], v[52:53], s[72:73], 1.0 op_sel_hi:[1,0,0]
	v_pk_mul_f32 v[52:53], v[52:53], v[52:53]
	v_rcp_f32_e32 v54, v54
	v_rcp_f32_e32 v55, v55
	v_pk_mul_f32 v[52:53], v[52:53], s[84:85] op_sel_hi:[1,0]
	v_pk_fma_f32 v[56:57], v[54:55], s[74:75], v[42:43] op_sel_hi:[1,0,0]
	s_nop 0
	v_pk_fma_f32 v[56:57], v[54:55], v[56:57], s[78:79] op_sel_hi:[1,1,0]
	v_exp_f32_e32 v52, v52
	v_exp_f32_e32 v53, v53
	v_pk_fma_f32 v[56:57], v[54:55], v[56:57], s[80:81] op_sel_hi:[1,1,0]
	s_nop 0
	v_pk_fma_f32 v[56:57], v[54:55], v[56:57], s[82:83] op_sel_hi:[1,1,0]
	s_nop 0
	v_pk_mul_f32 v[54:55], v[54:55], v[56:57]
	s_nop 0
	v_pk_fma_f32 v[52:53], v[52:53], v[54:55], 1.0 op_sel_hi:[1,1,0] neg_lo:[1,0,0] neg_hi:[1,0,0]
	s_nop 0
	v_bfi_b32 v51, s34, v53, v51
	v_bfi_b32 v50, s34, v52, v50
	v_pk_add_f32 v[50:51], v[50:51], 1.0 op_sel_hi:[1,0]
	s_nop 0
	v_pk_mul_f32 v[36:37], v[36:37], v[50:51]
	v_lshlrev_b32_e32 v50, 16, v33
	v_and_b32_e32 v51, 0xffff0000, v33
	v_pk_mul_f32 v[36:37], v[36:37], v[50:51]
	v_lshlrev_b32_e32 v50, 16, v38
	v_cvt_pk_bf16_f32 v33, v36, v37
	v_lshlrev_b32_e32 v36, 16, v61
	v_and_b32_e32 v37, 0xffff0000, v61
	v_pk_mul_f32 v[36:37], v[230:231], v[36:37]
	v_and_b32_e32 v51, 0xffff0000, v38
	v_pk_fma_f32 v[36:37], v[242:243], v[50:51], v[36:37]
	v_lshlrev_b32_e32 v50, 16, v64
	v_and_b32_e32 v51, 0xffff0000, v64
	v_pk_fma_f32 v[36:37], v[250:251], v[50:51], v[36:37]
	v_lshlrev_b32_e32 v38, 16, v39
	v_pk_add_f32 v[36:37], v[214:215], v[36:37]
	v_and_b32_e32 v39, 0xffff0000, v39
	v_pk_mul_f32 v[50:51], v[36:37], s[70:71] op_sel_hi:[1,0]
	v_pk_mul_f32 v[36:37], v[36:37], 0.5 op_sel_hi:[1,0]
	v_and_b32_e32 v52, 0x7fffffff, v50
	v_and_b32_e32 v53, 0x7fffffff, v51
	v_pk_fma_f32 v[54:55], v[52:53], s[72:73], 1.0 op_sel_hi:[1,0,0]
	v_pk_mul_f32 v[52:53], v[52:53], v[52:53]
	v_rcp_f32_e32 v54, v54
	v_rcp_f32_e32 v55, v55
	v_pk_mul_f32 v[52:53], v[52:53], s[84:85] op_sel_hi:[1,0]
	v_pk_fma_f32 v[56:57], v[54:55], s[74:75], v[42:43] op_sel_hi:[1,0,0]
	s_nop 0
	v_pk_fma_f32 v[56:57], v[54:55], v[56:57], s[78:79] op_sel_hi:[1,1,0]
	v_exp_f32_e32 v52, v52
	v_exp_f32_e32 v53, v53
	v_pk_fma_f32 v[56:57], v[54:55], v[56:57], s[80:81] op_sel_hi:[1,1,0]
	s_nop 0
	v_pk_fma_f32 v[56:57], v[54:55], v[56:57], s[82:83] op_sel_hi:[1,1,0]
	s_nop 0
	v_pk_mul_f32 v[54:55], v[54:55], v[56:57]
	s_nop 0
	v_pk_fma_f32 v[52:53], v[52:53], v[54:55], 1.0 op_sel_hi:[1,1,0] neg_lo:[1,0,0] neg_hi:[1,0,0]
	s_nop 0
	v_bfi_b32 v51, s34, v53, v51
	v_bfi_b32 v50, s34, v52, v50
	v_pk_add_f32 v[50:51], v[50:51], 1.0 op_sel_hi:[1,0]
	s_nop 0
	v_pk_mul_f32 v[36:37], v[36:37], v[50:51]
	v_lshlrev_b32_e32 v50, 16, v34
	v_and_b32_e32 v51, 0xffff0000, v34
	v_pk_mul_f32 v[36:37], v[36:37], v[50:51]
	s_nop 0
	v_cvt_pk_bf16_f32 v34, v36, v37
	v_lshlrev_b32_e32 v36, 16, v60
	v_and_b32_e32 v37, 0xffff0000, v60
	v_pk_mul_f32 v[36:37], v[232:233], v[36:37]
	s_nop 0
	v_pk_fma_f32 v[36:37], v[244:245], v[38:39], v[36:37]
	v_lshlrev_b32_e32 v38, 16, v63
	v_and_b32_e32 v39, 0xffff0000, v63
	v_pk_fma_f32 v[36:37], v[252:253], v[38:39], v[36:37]
	s_nop 0
	v_pk_add_f32 v[36:37], v[216:217], v[36:37]
	s_nop 0
	v_pk_mul_f32 v[38:39], v[36:37], s[70:71] op_sel_hi:[1,0]
	v_pk_mul_f32 v[36:37], v[36:37], 0.5 op_sel_hi:[1,0]
	v_and_b32_e32 v50, 0x7fffffff, v38
	v_and_b32_e32 v51, 0x7fffffff, v39
	v_pk_fma_f32 v[52:53], v[50:51], s[72:73], 1.0 op_sel_hi:[1,0,0]
	v_pk_mul_f32 v[50:51], v[50:51], v[50:51]
	v_rcp_f32_e32 v52, v52
	v_rcp_f32_e32 v53, v53
	v_pk_mul_f32 v[50:51], v[50:51], s[84:85] op_sel_hi:[1,0]
	v_pk_fma_f32 v[42:43], v[52:53], s[74:75], v[42:43] op_sel_hi:[1,0,0]
	s_nop 0
	v_pk_fma_f32 v[42:43], v[52:53], v[42:43], s[78:79] op_sel_hi:[1,1,0]
	v_exp_f32_e32 v50, v50
	v_exp_f32_e32 v51, v51
	v_pk_fma_f32 v[42:43], v[52:53], v[42:43], s[80:81] op_sel_hi:[1,1,0]
	s_nop 0
	v_pk_fma_f32 v[42:43], v[52:53], v[42:43], s[82:83] op_sel_hi:[1,1,0]
	s_nop 0
	v_pk_mul_f32 v[42:43], v[52:53], v[42:43]
	s_nop 0
	v_pk_fma_f32 v[42:43], v[50:51], v[42:43], 1.0 op_sel_hi:[1,1,0] neg_lo:[1,0,0] neg_hi:[1,0,0]
	s_nop 0
	v_bfi_b32 v39, s34, v43, v39
	v_bfi_b32 v38, s34, v42, v38
	v_pk_add_f32 v[38:39], v[38:39], 1.0 op_sel_hi:[1,0]
	s_nop 0
	v_pk_mul_f32 v[36:37], v[36:37], v[38:39]
	v_lshlrev_b32_e32 v38, 16, v35
	v_and_b32_e32 v39, 0xffff0000, v35
	v_pk_mul_f32 v[36:37], v[36:37], v[38:39]
	s_nop 0
	v_cvt_pk_bf16_f32 v35, v36, v37
	v_mad_i64_i32 v[36:37], s[94:95], v48, s35, v[40:41]
	global_store_dwordx4 v[36:37], v[32:35], off nt
.LBB0_2310:
	s_or_b64 exec, exec, s[2:3]
	v_cmp_gt_u32_e32 vcc, s50, v45
	v_cmp_gt_i32_e64 s[2:3], s81, v46
	s_and_b64 s[94:95], vcc, s[2:3]
	s_and_saveexec_b64 s[2:3], s[94:95]
	s_cbranch_execz .LBB0_2307
	ds_read_b128 v[48:51], v47 offset:8432
	ds_read_b128 v[36:39], v47 offset:8704
	ds_read_b128 v[52:55], v47 offset:8976
	v_and_b32_e32 v42, 0xfff, v46
	v_cmp_eq_u32_e32 vcc, 0, v42
	v_add_u32_e32 v32, 0x13200, v47
	ds_read_b128 v[32:35], v32
	s_waitcnt lgkmcnt(3)
	v_cndmask_b32_e64 v43, v48, 0, vcc
	v_cndmask_b32_e64 v47, v49, 0, vcc
	v_cndmask_b32_e64 v58, v51, 0, vcc
	v_cndmask_b32_e64 v59, v50, 0, vcc
	v_cmp_eq_u32_e32 vcc, s79, v42
	v_lshlrev_b32_e32 v42, 16, v43
	v_and_b32_e32 v43, 0xffff0000, v43
	s_waitcnt lgkmcnt(1)
	v_cndmask_b32_e64 v50, v52, 0, vcc
	v_pk_mul_f32 v[42:43], v[234:235], v[42:43]
	v_lshlrev_b32_e32 v48, 16, v36
	v_and_b32_e32 v49, 0xffff0000, v36
	v_pk_fma_f32 v[42:43], v[238:239], v[48:49], v[42:43]
	v_lshlrev_b32_e32 v48, 16, v50
	v_and_b32_e32 v49, 0xffff0000, v50
	v_pk_fma_f32 v[42:43], v[246:247], v[48:49], v[42:43]
	v_cndmask_b32_e64 v60, v53, 0, vcc
	v_pk_add_f32 v[48:49], v[218:219], v[42:43]
	v_cndmask_b32_e64 v61, v55, 0, vcc
	v_pk_mul_f32 v[50:51], v[48:49], s[70:71] op_sel_hi:[1,0]
	v_cndmask_b32_e64 v62, v54, 0, vcc
	v_and_b32_e32 v52, 0x7fffffff, v50
	v_and_b32_e32 v53, 0x7fffffff, v51
	v_pk_fma_f32 v[42:43], v[52:53], s[72:73], 1.0 op_sel_hi:[1,0,0]
	v_pk_mul_f32 v[52:53], v[52:53], v[52:53]
	v_rcp_f32_e32 v54, v42
	v_rcp_f32_e32 v55, v43
	v_mov_b64_e32 v[42:43], s[76:77]
	v_pk_mul_f32 v[52:53], v[52:53], s[84:85] op_sel_hi:[1,0]
	v_pk_mul_f32 v[48:49], v[48:49], 0.5 op_sel_hi:[1,0]
	v_pk_fma_f32 v[56:57], v[54:55], s[74:75], v[42:43] op_sel_hi:[1,0,0]
	v_exp_f32_e32 v52, v52
	v_pk_fma_f32 v[56:57], v[54:55], v[56:57], s[78:79] op_sel_hi:[1,1,0]
	v_exp_f32_e32 v53, v53
	v_pk_fma_f32 v[56:57], v[54:55], v[56:57], s[80:81] op_sel_hi:[1,1,0]
	v_lshlrev_b32_e32 v36, 16, v37
	v_pk_fma_f32 v[56:57], v[54:55], v[56:57], s[82:83] op_sel_hi:[1,1,0]
	v_and_b32_e32 v37, 0xffff0000, v37
	v_pk_mul_f32 v[54:55], v[54:55], v[56:57]
	s_nop 0
	v_pk_fma_f32 v[52:53], v[52:53], v[54:55], 1.0 op_sel_hi:[1,1,0] neg_lo:[1,0,0] neg_hi:[1,0,0]
	s_nop 0
	v_bfi_b32 v51, s34, v53, v51
	v_bfi_b32 v50, s34, v52, v50
	v_pk_add_f32 v[50:51], v[50:51], 1.0 op_sel_hi:[1,0]
	s_nop 0
	v_pk_mul_f32 v[48:49], v[48:49], v[50:51]
	s_waitcnt lgkmcnt(0)
	v_lshlrev_b32_e32 v50, 16, v32
	v_and_b32_e32 v51, 0xffff0000, v32
	v_pk_mul_f32 v[48:49], v[48:49], v[50:51]
	s_nop 0
	v_cvt_pk_bf16_f32 v32, v48, v49
	v_lshlrev_b32_e32 v48, 16, v47
	v_and_b32_e32 v49, 0xffff0000, v47
	v_pk_mul_f32 v[48:49], v[236:237], v[48:49]
	s_nop 0
	v_pk_fma_f32 v[36:37], v[240:241], v[36:37], v[48:49]
	v_lshlrev_b32_e32 v48, 16, v60
	v_and_b32_e32 v49, 0xffff0000, v60
	v_pk_fma_f32 v[36:37], v[248:249], v[48:49], v[36:37]
	s_nop 0
	v_pk_add_f32 v[36:37], v[220:221], v[36:37]
	s_nop 0
	v_pk_mul_f32 v[48:49], v[36:37], s[70:71] op_sel_hi:[1,0]
	v_pk_mul_f32 v[36:37], v[36:37], 0.5 op_sel_hi:[1,0]
	v_and_b32_e32 v50, 0x7fffffff, v48
	v_and_b32_e32 v51, 0x7fffffff, v49
	v_pk_fma_f32 v[52:53], v[50:51], s[72:73], 1.0 op_sel_hi:[1,0,0]
	v_pk_mul_f32 v[50:51], v[50:51], v[50:51]
	v_rcp_f32_e32 v52, v52
	v_rcp_f32_e32 v53, v53
	v_pk_mul_f32 v[50:51], v[50:51], s[84:85] op_sel_hi:[1,0]
	v_pk_fma_f32 v[54:55], v[52:53], s[74:75], v[42:43] op_sel_hi:[1,0,0]
	s_nop 0
	v_pk_fma_f32 v[54:55], v[52:53], v[54:55], s[78:79] op_sel_hi:[1,1,0]
	v_exp_f32_e32 v50, v50
	v_exp_f32_e32 v51, v51
	v_pk_fma_f32 v[54:55], v[52:53], v[54:55], s[80:81] op_sel_hi:[1,1,0]
	s_nop 0
	v_pk_fma_f32 v[54:55], v[52:53], v[54:55], s[82:83] op_sel_hi:[1,1,0]
	s_nop 0
	v_pk_mul_f32 v[52:53], v[52:53], v[54:55]
	s_nop 0
	v_pk_fma_f32 v[50:51], v[50:51], v[52:53], 1.0 op_sel_hi:[1,1,0] neg_lo:[1,0,0] neg_hi:[1,0,0]
	s_nop 0
	v_bfi_b32 v49, s34, v51, v49
	v_bfi_b32 v48, s34, v50, v48
	v_pk_add_f32 v[48:49], v[48:49], 1.0 op_sel_hi:[1,0]
	s_nop 0
	v_pk_mul_f32 v[36:37], v[36:37], v[48:49]
	v_lshlrev_b32_e32 v48, 16, v33
	v_and_b32_e32 v49, 0xffff0000, v33
	v_pk_mul_f32 v[36:37], v[36:37], v[48:49]
	v_lshlrev_b32_e32 v48, 16, v38
	v_cvt_pk_bf16_f32 v33, v36, v37
	v_lshlrev_b32_e32 v36, 16, v59
	v_and_b32_e32 v37, 0xffff0000, v59
	v_pk_mul_f32 v[36:37], v[230:231], v[36:37]
	v_and_b32_e32 v49, 0xffff0000, v38
	v_pk_fma_f32 v[36:37], v[242:243], v[48:49], v[36:37]
	v_lshlrev_b32_e32 v48, 16, v62
	v_and_b32_e32 v49, 0xffff0000, v62
	v_pk_fma_f32 v[36:37], v[250:251], v[48:49], v[36:37]
	v_lshlrev_b32_e32 v38, 16, v39
	v_pk_add_f32 v[36:37], v[214:215], v[36:37]
	v_and_b32_e32 v39, 0xffff0000, v39
	v_pk_mul_f32 v[48:49], v[36:37], s[70:71] op_sel_hi:[1,0]
	v_pk_mul_f32 v[36:37], v[36:37], 0.5 op_sel_hi:[1,0]
	v_and_b32_e32 v50, 0x7fffffff, v48
	v_and_b32_e32 v51, 0x7fffffff, v49
	v_pk_fma_f32 v[52:53], v[50:51], s[72:73], 1.0 op_sel_hi:[1,0,0]
	v_pk_mul_f32 v[50:51], v[50:51], v[50:51]
	v_rcp_f32_e32 v52, v52
	v_rcp_f32_e32 v53, v53
	v_pk_mul_f32 v[50:51], v[50:51], s[84:85] op_sel_hi:[1,0]
	v_pk_fma_f32 v[54:55], v[52:53], s[74:75], v[42:43] op_sel_hi:[1,0,0]
	s_nop 0
	v_pk_fma_f32 v[54:55], v[52:53], v[54:55], s[78:79] op_sel_hi:[1,1,0]
	v_exp_f32_e32 v50, v50
	v_exp_f32_e32 v51, v51
	v_pk_fma_f32 v[54:55], v[52:53], v[54:55], s[80:81] op_sel_hi:[1,1,0]
	s_nop 0
	v_pk_fma_f32 v[54:55], v[52:53], v[54:55], s[82:83] op_sel_hi:[1,1,0]
	s_nop 0
	v_pk_mul_f32 v[52:53], v[52:53], v[54:55]
	s_nop 0
	v_pk_fma_f32 v[50:51], v[50:51], v[52:53], 1.0 op_sel_hi:[1,1,0] neg_lo:[1,0,0] neg_hi:[1,0,0]
	s_nop 0
	v_bfi_b32 v49, s34, v51, v49
	v_bfi_b32 v48, s34, v50, v48
	v_pk_add_f32 v[48:49], v[48:49], 1.0 op_sel_hi:[1,0]
	s_nop 0
	v_pk_mul_f32 v[36:37], v[36:37], v[48:49]
	v_lshlrev_b32_e32 v48, 16, v34
	v_and_b32_e32 v49, 0xffff0000, v34
	v_pk_mul_f32 v[36:37], v[36:37], v[48:49]
	s_nop 0
	v_cvt_pk_bf16_f32 v34, v36, v37
	v_lshlrev_b32_e32 v36, 16, v58
	v_and_b32_e32 v37, 0xffff0000, v58
	v_pk_mul_f32 v[36:37], v[232:233], v[36:37]
	s_nop 0
	v_pk_fma_f32 v[36:37], v[244:245], v[38:39], v[36:37]
	v_lshlrev_b32_e32 v38, 16, v61
	v_and_b32_e32 v39, 0xffff0000, v61
	v_pk_fma_f32 v[36:37], v[252:253], v[38:39], v[36:37]
	s_nop 0
	v_pk_add_f32 v[36:37], v[216:217], v[36:37]
	s_nop 0
	v_pk_mul_f32 v[38:39], v[36:37], s[70:71] op_sel_hi:[1,0]
	v_pk_mul_f32 v[36:37], v[36:37], 0.5 op_sel_hi:[1,0]
	v_and_b32_e32 v48, 0x7fffffff, v38
	v_and_b32_e32 v49, 0x7fffffff, v39
	v_pk_fma_f32 v[50:51], v[48:49], s[72:73], 1.0 op_sel_hi:[1,0,0]
	v_pk_mul_f32 v[48:49], v[48:49], v[48:49]
	v_rcp_f32_e32 v50, v50
	v_rcp_f32_e32 v51, v51
	v_pk_mul_f32 v[48:49], v[48:49], s[84:85] op_sel_hi:[1,0]
	v_pk_fma_f32 v[42:43], v[50:51], s[74:75], v[42:43] op_sel_hi:[1,0,0]
	s_nop 0
	v_pk_fma_f32 v[42:43], v[50:51], v[42:43], s[78:79] op_sel_hi:[1,1,0]
	v_exp_f32_e32 v48, v48
	v_exp_f32_e32 v49, v49
	v_pk_fma_f32 v[42:43], v[50:51], v[42:43], s[80:81] op_sel_hi:[1,1,0]
	s_nop 0
	v_pk_fma_f32 v[42:43], v[50:51], v[42:43], s[82:83] op_sel_hi:[1,1,0]
	s_nop 0
	v_pk_mul_f32 v[42:43], v[50:51], v[42:43]
	s_nop 0
	v_pk_fma_f32 v[42:43], v[48:49], v[42:43], 1.0 op_sel_hi:[1,1,0] neg_lo:[1,0,0] neg_hi:[1,0,0]
	s_nop 0
	v_bfi_b32 v39, s34, v43, v39
	v_bfi_b32 v38, s34, v42, v38
	v_pk_add_f32 v[38:39], v[38:39], 1.0 op_sel_hi:[1,0]
	s_nop 0
	v_pk_mul_f32 v[36:37], v[36:37], v[38:39]
	v_lshlrev_b32_e32 v38, 16, v35
	v_and_b32_e32 v39, 0xffff0000, v35
	v_pk_mul_f32 v[36:37], v[36:37], v[38:39]
	s_nop 0
	v_cvt_pk_bf16_f32 v35, v36, v37
	v_mad_i64_i32 v[36:37], s[94:95], v46, s35, v[40:41]
	global_store_dwordx4 v[36:37], v[32:35], off nt
	s_branch .LBB0_2307
